# hyena: hand-written scalar-f32 radix-4 forward middle passes (LQ 10..2) with loads pipelined one butterfly ahead
# speedup vs baseline: 1.0134x; 1.0114x over previous
; HD float2 cmul(float2 a, float2 b){ return make_float2(a.x*b.x - a.y*b.y, a.x*b.y + a.y*b.x); }
; HD float2 cmulc(float2 a, float2 b){ return make_float2(a.x*b.x + a.y*b.y, a.y*b.x - a.x*b.y); }
; template<bool INV, bool NOTW>
; HD void bf4c(float2* Z, int i0, int i1, int i2, int i3, float2 w1, float2 w2, float2 w3){
;   float2 a0=Z[i0], a1=Z[i1], a2=Z[i2], a3=Z[i3];
;   if (INV && !NOTW){ a1=cmulc(a1,w1); a2=cmulc(a2,w2); a3=cmulc(a3,w3); }
;   float2 s02=make_float2(a0.x+a2.x,a0.y+a2.y), d02=make_float2(a0.x-a2.x,a0.y-a2.y);
;   float2 s13=make_float2(a1.x+a3.x,a1.y+a3.y), d13=make_float2(a1.x-a3.x,a1.y-a3.y);
;   float2 y0=make_float2(s02.x+s13.x,s02.y+s13.y), y2=make_float2(s02.x-s13.x,s02.y-s13.y);
;   float2 ym=make_float2(d02.x+d13.y,d02.y-d13.x);
;   float2 yp=make_float2(d02.x-d13.y,d02.y+d13.x);
;   float2 y1, y3;
;   if (INV){ y1=yp; y3=ym; } else if (NOTW){ y1=ym; y3=yp; } else { y1=cmul(ym,w1); y2=cmul(y2,w2); y3=cmul(yp,w3); }
;   Z[i0]=y0; Z[i1]=y1; Z[i2]=y2; Z[i3]=y3;
; }
; template<bool INV, int LQ, bool BARRIER=true>
; HD void fft_pass(float2* Z, const float2* twA, const float2* twB, int tid){
;     ...
;   } else if (LQ==10){
;     _Pragma("unroll") for (int e=0;e<2;++e){ int j=tid+512*e; int k=j*tws;
;       float2 w1=cmul(twA[k>>6],twB[k&63]), w2=cmul(w1,w1), w3=cmul(w2,w1);
;       _Pragma("unroll") for (int ip=0;ip<4;++ip){ int base=ip*4096+j; bf4c<INV,false>(Z,base,base+q,base+2*q,base+3*q,w1,w2,w3); } }
.Lmy_pf_skipb:
	v_add_u32_e32 v226, 0, v154
	v_lshrrev_b32_e32 v224, 4, v226
	v_lshlrev_b32_e32 v224, 3, v224
	v_add_u32_e32 v224, 0x20800, v224
	v_and_b32_e32 v225, 15, v226
	v_lshlrev_b32_e32 v225, 5, v225
	v_add_u32_e32 v225, 0x20a00, v225
	ds_read_b64 v[238:239], v224
	ds_read_b64 v[240:241], v225
	s_waitcnt lgkmcnt(0)
	v_mul_f32_e32 v227, v239, v241
	v_fma_f32 v16, v238, v240, -v227
	v_mul_f32_e32 v227, v239, v240
	v_fma_f32 v17, v238, v241, v227
	v_mul_f32_e32 v227, v17, v17
	v_fma_f32 v18, v16, v16, -v227
	v_mul_f32_e32 v227, v17, v16
	v_fma_f32 v19, v16, v17, v227
	v_mul_f32_e32 v227, v19, v17
	v_fma_f32 v20, v18, v16, -v227
	v_mul_f32_e32 v227, v19, v16
	v_fma_f32 v21, v18, v17, v227
	v_lshlrev_b32_e32 v222, 3, v154
	v_add_u32_e32 v223, 0x10000, v222
	ds_read_b64 v[0:1], v222 offset:0
	ds_read_b64 v[2:3], v222 offset:8192
	ds_read_b64 v[4:5], v222 offset:16384
	ds_read_b64 v[6:7], v222 offset:24576
	ds_read_b64 v[8:9], v222 offset:32768
	ds_read_b64 v[10:11], v222 offset:40960
	ds_read_b64 v[12:13], v222 offset:49152
	ds_read_b64 v[14:15], v222 offset:57344
	s_waitcnt lgkmcnt(4)
	v_add_f32_e32 v22, v0, v4
	v_sub_f32_e32 v24, v0, v4
	v_add_f32_e32 v26, v2, v6
	v_sub_f32_e32 v28, v2, v6
	v_add_f32_e32 v23, v1, v5
	v_sub_f32_e32 v25, v1, v5
	v_add_f32_e32 v27, v3, v7
	v_sub_f32_e32 v29, v3, v7
	v_add_f32_e32 v80, v22, v26
	v_add_f32_e32 v81, v23, v27
	ds_write_b64 v222, v[80:81] offset:0
	v_sub_f32_e32 v242, v22, v26
	v_sub_f32_e32 v243, v23, v27
	v_add_f32_e32 v244, v24, v29
	v_sub_f32_e32 v245, v25, v28
	v_sub_f32_e32 v246, v24, v29
	v_add_f32_e32 v247, v25, v28
	v_mul_f32_e32 v227, v245, v17
	v_fma_f32 v82, v244, v16, -v227
	v_mul_f32_e32 v227, v245, v16
	v_fma_f32 v83, v244, v17, v227
	ds_write_b64 v222, v[82:83] offset:8192
	v_mul_f32_e32 v227, v243, v19
	v_fma_f32 v84, v242, v18, -v227
	v_mul_f32_e32 v227, v243, v18
	v_fma_f32 v85, v242, v19, v227
	ds_write_b64 v222, v[84:85] offset:16384
	v_mul_f32_e32 v227, v247, v21
	v_fma_f32 v236, v246, v20, -v227
	v_mul_f32_e32 v227, v247, v20
	v_fma_f32 v237, v246, v21, v227
	ds_write_b64 v222, v[236:237] offset:24576
	ds_read_b64 v[0:1], v223 offset:0
	ds_read_b64 v[2:3], v223 offset:8192
	ds_read_b64 v[4:5], v223 offset:16384
	ds_read_b64 v[6:7], v223 offset:24576
	s_waitcnt lgkmcnt(8)
	v_add_f32_e32 v22, v8, v12
	v_sub_f32_e32 v24, v8, v12
	v_add_f32_e32 v26, v10, v14
	v_sub_f32_e32 v28, v10, v14
	v_add_f32_e32 v23, v9, v13
	v_sub_f32_e32 v25, v9, v13
	v_add_f32_e32 v27, v11, v15
	v_sub_f32_e32 v29, v11, v15
	v_add_f32_e32 v80, v22, v26
	v_add_f32_e32 v81, v23, v27
	ds_write_b64 v222, v[80:81] offset:32768
	v_sub_f32_e32 v242, v22, v26
	v_sub_f32_e32 v243, v23, v27
	v_add_f32_e32 v244, v24, v29
	v_sub_f32_e32 v245, v25, v28
	v_sub_f32_e32 v246, v24, v29
	v_add_f32_e32 v247, v25, v28
	v_mul_f32_e32 v227, v245, v17
	v_fma_f32 v82, v244, v16, -v227
	v_mul_f32_e32 v227, v245, v16
	v_fma_f32 v83, v244, v17, v227
	ds_write_b64 v222, v[82:83] offset:40960
	v_mul_f32_e32 v227, v243, v19
	v_fma_f32 v84, v242, v18, -v227
	v_mul_f32_e32 v227, v243, v18
	v_fma_f32 v85, v242, v19, v227
	ds_write_b64 v222, v[84:85] offset:49152
	v_mul_f32_e32 v227, v247, v21
	v_fma_f32 v236, v246, v20, -v227
	v_mul_f32_e32 v227, v247, v20
	v_fma_f32 v237, v246, v21, v227
	ds_write_b64 v222, v[236:237] offset:57344
	ds_read_b64 v[8:9], v223 offset:32768
	ds_read_b64 v[10:11], v223 offset:40960
	ds_read_b64 v[12:13], v223 offset:49152
	ds_read_b64 v[14:15], v223 offset:57344
	s_waitcnt lgkmcnt(8)
	v_add_f32_e32 v22, v0, v4
	v_sub_f32_e32 v24, v0, v4
	v_add_f32_e32 v26, v2, v6
	v_sub_f32_e32 v28, v2, v6
	v_add_f32_e32 v23, v1, v5
	v_sub_f32_e32 v25, v1, v5
	v_add_f32_e32 v27, v3, v7
	v_sub_f32_e32 v29, v3, v7
	v_add_f32_e32 v80, v22, v26
	v_add_f32_e32 v81, v23, v27
	ds_write_b64 v223, v[80:81] offset:0
	v_sub_f32_e32 v242, v22, v26
	v_sub_f32_e32 v243, v23, v27
	v_add_f32_e32 v244, v24, v29
	v_sub_f32_e32 v245, v25, v28
	v_sub_f32_e32 v246, v24, v29
	v_add_f32_e32 v247, v25, v28
	v_mul_f32_e32 v227, v245, v17
	v_fma_f32 v82, v244, v16, -v227
	v_mul_f32_e32 v227, v245, v16
	v_fma_f32 v83, v244, v17, v227
	ds_write_b64 v223, v[82:83] offset:8192
	v_mul_f32_e32 v227, v243, v19
	v_fma_f32 v84, v242, v18, -v227
	v_mul_f32_e32 v227, v243, v18
	v_fma_f32 v85, v242, v19, v227
	ds_write_b64 v223, v[84:85] offset:16384
	v_mul_f32_e32 v227, v247, v21
	v_fma_f32 v236, v246, v20, -v227
	v_mul_f32_e32 v227, v247, v20
	v_fma_f32 v237, v246, v21, v227
	ds_write_b64 v223, v[236:237] offset:24576
	s_waitcnt lgkmcnt(4)
	v_add_f32_e32 v22, v8, v12
	v_sub_f32_e32 v24, v8, v12
	v_add_f32_e32 v26, v10, v14
	v_sub_f32_e32 v28, v10, v14
	v_add_f32_e32 v23, v9, v13
	v_sub_f32_e32 v25, v9, v13
	v_add_f32_e32 v27, v11, v15
	v_sub_f32_e32 v29, v11, v15
	v_add_f32_e32 v80, v22, v26
	v_add_f32_e32 v81, v23, v27
	ds_write_b64 v223, v[80:81] offset:32768
	v_sub_f32_e32 v242, v22, v26
	v_sub_f32_e32 v243, v23, v27
	v_add_f32_e32 v244, v24, v29
	v_sub_f32_e32 v245, v25, v28
	v_sub_f32_e32 v246, v24, v29
	v_add_f32_e32 v247, v25, v28
	v_mul_f32_e32 v227, v245, v17
	v_fma_f32 v82, v244, v16, -v227
	v_mul_f32_e32 v227, v245, v16
	v_fma_f32 v83, v244, v17, v227
	ds_write_b64 v223, v[82:83] offset:40960
	v_mul_f32_e32 v227, v243, v19
	v_fma_f32 v84, v242, v18, -v227
	v_mul_f32_e32 v227, v243, v18
	v_fma_f32 v85, v242, v19, v227
	ds_write_b64 v223, v[84:85] offset:49152
	v_mul_f32_e32 v227, v247, v21
	v_fma_f32 v236, v246, v20, -v227
	v_mul_f32_e32 v227, v247, v20
	v_fma_f32 v237, v246, v21, v227
	ds_write_b64 v223, v[236:237] offset:57344
	s_nop 0
	v_add_u32_e32 v226, 512, v154
	v_lshrrev_b32_e32 v224, 4, v226
	v_lshlrev_b32_e32 v224, 3, v224
	v_add_u32_e32 v224, 0x20800, v224
	v_and_b32_e32 v225, 15, v226
	v_lshlrev_b32_e32 v225, 5, v225
	v_add_u32_e32 v225, 0x20a00, v225
	ds_read_b64 v[238:239], v224
	ds_read_b64 v[240:241], v225
	s_waitcnt lgkmcnt(0)
; HD float2 cmul(float2 a, float2 b){ return make_float2(a.x*b.x - a.y*b.y, a.x*b.y + a.y*b.x); }
; HD float2 cmulc(float2 a, float2 b){ return make_float2(a.x*b.x + a.y*b.y, a.y*b.x - a.x*b.y); }
; template<bool INV, bool NOTW>
; HD void bf4c(float2* Z, int i0, int i1, int i2, int i3, float2 w1, float2 w2, float2 w3){
;   float2 a0=Z[i0], a1=Z[i1], a2=Z[i2], a3=Z[i3];
;   if (INV && !NOTW){ a1=cmulc(a1,w1); a2=cmulc(a2,w2); a3=cmulc(a3,w3); }
;   float2 s02=make_float2(a0.x+a2.x,a0.y+a2.y), d02=make_float2(a0.x-a2.x,a0.y-a2.y);
;   float2 s13=make_float2(a1.x+a3.x,a1.y+a3.y), d13=make_float2(a1.x-a3.x,a1.y-a3.y);
;   float2 y0=make_float2(s02.x+s13.x,s02.y+s13.y), y2=make_float2(s02.x-s13.x,s02.y-s13.y);
;   float2 ym=make_float2(d02.x+d13.y,d02.y-d13.x);
;   float2 yp=make_float2(d02.x-d13.y,d02.y+d13.x);
;   float2 y1, y3;
;   if (INV){ y1=yp; y3=ym; } else if (NOTW){ y1=ym; y3=yp; } else { y1=cmul(ym,w1); y2=cmul(y2,w2); y3=cmul(yp,w3); }
;   Z[i0]=y0; Z[i1]=y1; Z[i2]=y2; Z[i3]=y3;
; }
; template<bool INV, int LQ, bool BARRIER=true>
; HD void fft_pass(float2* Z, const float2* twA, const float2* twB, int tid){
;     ...
;   } else if (LQ==10){
;     _Pragma("unroll") for (int e=0;e<2;++e){ int j=tid+512*e; int k=j*tws;
;       float2 w1=cmul(twA[k>>6],twB[k&63]), w2=cmul(w1,w1), w3=cmul(w2,w1);
;       _Pragma("unroll") for (int ip=0;ip<4;++ip){ int base=ip*4096+j; bf4c<INV,false>(Z,base,base+q,base+2*q,base+3*q,w1,w2,w3); } }
	v_mul_f32_e32 v227, v239, v241
	v_fma_f32 v16, v238, v240, -v227
	v_mul_f32_e32 v227, v239, v240
	v_fma_f32 v17, v238, v241, v227
	v_mul_f32_e32 v227, v17, v17
	v_fma_f32 v18, v16, v16, -v227
	v_mul_f32_e32 v227, v17, v16
	v_fma_f32 v19, v16, v17, v227
	v_mul_f32_e32 v227, v19, v17
	v_fma_f32 v20, v18, v16, -v227
	v_mul_f32_e32 v227, v19, v16
	v_fma_f32 v21, v18, v17, v227
	ds_read_b64 v[0:1], v222 offset:4096
	ds_read_b64 v[2:3], v222 offset:12288
	ds_read_b64 v[4:5], v222 offset:20480
	ds_read_b64 v[6:7], v222 offset:28672
	ds_read_b64 v[8:9], v222 offset:36864
	ds_read_b64 v[10:11], v222 offset:45056
	ds_read_b64 v[12:13], v222 offset:53248
	ds_read_b64 v[14:15], v222 offset:61440
	s_waitcnt lgkmcnt(4)
	v_add_f32_e32 v22, v0, v4
	v_sub_f32_e32 v24, v0, v4
	v_add_f32_e32 v26, v2, v6
	v_sub_f32_e32 v28, v2, v6
	v_add_f32_e32 v23, v1, v5
	v_sub_f32_e32 v25, v1, v5
	v_add_f32_e32 v27, v3, v7
	v_sub_f32_e32 v29, v3, v7
	v_add_f32_e32 v80, v22, v26
	v_add_f32_e32 v81, v23, v27
	ds_write_b64 v222, v[80:81] offset:4096
	v_sub_f32_e32 v242, v22, v26
	v_sub_f32_e32 v243, v23, v27
	v_add_f32_e32 v244, v24, v29
	v_sub_f32_e32 v245, v25, v28
	v_sub_f32_e32 v246, v24, v29
	v_add_f32_e32 v247, v25, v28
	v_mul_f32_e32 v227, v245, v17
	v_fma_f32 v82, v244, v16, -v227
	v_mul_f32_e32 v227, v245, v16
	v_fma_f32 v83, v244, v17, v227
	ds_write_b64 v222, v[82:83] offset:12288
	v_mul_f32_e32 v227, v243, v19
	v_fma_f32 v84, v242, v18, -v227
	v_mul_f32_e32 v227, v243, v18
	v_fma_f32 v85, v242, v19, v227
	ds_write_b64 v222, v[84:85] offset:20480
	v_mul_f32_e32 v227, v247, v21
	v_fma_f32 v236, v246, v20, -v227
	v_mul_f32_e32 v227, v247, v20
	v_fma_f32 v237, v246, v21, v227
	ds_write_b64 v222, v[236:237] offset:28672
	ds_read_b64 v[0:1], v223 offset:4096
	ds_read_b64 v[2:3], v223 offset:12288
	ds_read_b64 v[4:5], v223 offset:20480
	ds_read_b64 v[6:7], v223 offset:28672
	s_waitcnt lgkmcnt(8)
	v_add_f32_e32 v22, v8, v12
	v_sub_f32_e32 v24, v8, v12
	v_add_f32_e32 v26, v10, v14
	v_sub_f32_e32 v28, v10, v14
	v_add_f32_e32 v23, v9, v13
	v_sub_f32_e32 v25, v9, v13
	v_add_f32_e32 v27, v11, v15
	v_sub_f32_e32 v29, v11, v15
	v_add_f32_e32 v80, v22, v26
	v_add_f32_e32 v81, v23, v27
	ds_write_b64 v222, v[80:81] offset:36864
	v_sub_f32_e32 v242, v22, v26
	v_sub_f32_e32 v243, v23, v27
	v_add_f32_e32 v244, v24, v29
	v_sub_f32_e32 v245, v25, v28
	v_sub_f32_e32 v246, v24, v29
	v_add_f32_e32 v247, v25, v28
	v_mul_f32_e32 v227, v245, v17
	v_fma_f32 v82, v244, v16, -v227
	v_mul_f32_e32 v227, v245, v16
	v_fma_f32 v83, v244, v17, v227
	ds_write_b64 v222, v[82:83] offset:45056
	v_mul_f32_e32 v227, v243, v19
	v_fma_f32 v84, v242, v18, -v227
	v_mul_f32_e32 v227, v243, v18
	v_fma_f32 v85, v242, v19, v227
	ds_write_b64 v222, v[84:85] offset:53248
	v_mul_f32_e32 v227, v247, v21
	v_fma_f32 v236, v246, v20, -v227
	v_mul_f32_e32 v227, v247, v20
	v_fma_f32 v237, v246, v21, v227
	ds_write_b64 v222, v[236:237] offset:61440
	ds_read_b64 v[8:9], v223 offset:36864
	ds_read_b64 v[10:11], v223 offset:45056
	ds_read_b64 v[12:13], v223 offset:53248
	ds_read_b64 v[14:15], v223 offset:61440
	s_waitcnt lgkmcnt(8)
	v_add_f32_e32 v22, v0, v4
	v_sub_f32_e32 v24, v0, v4
	v_add_f32_e32 v26, v2, v6
	v_sub_f32_e32 v28, v2, v6
	v_add_f32_e32 v23, v1, v5
	v_sub_f32_e32 v25, v1, v5
	v_add_f32_e32 v27, v3, v7
	v_sub_f32_e32 v29, v3, v7
	v_add_f32_e32 v80, v22, v26
	v_add_f32_e32 v81, v23, v27
	ds_write_b64 v223, v[80:81] offset:4096
	v_sub_f32_e32 v242, v22, v26
	v_sub_f32_e32 v243, v23, v27
	v_add_f32_e32 v244, v24, v29
	v_sub_f32_e32 v245, v25, v28
	v_sub_f32_e32 v246, v24, v29
	v_add_f32_e32 v247, v25, v28
	v_mul_f32_e32 v227, v245, v17
	v_fma_f32 v82, v244, v16, -v227
	v_mul_f32_e32 v227, v245, v16
	v_fma_f32 v83, v244, v17, v227
	ds_write_b64 v223, v[82:83] offset:12288
	v_mul_f32_e32 v227, v243, v19
	v_fma_f32 v84, v242, v18, -v227
	v_mul_f32_e32 v227, v243, v18
	v_fma_f32 v85, v242, v19, v227
	ds_write_b64 v223, v[84:85] offset:20480
	v_mul_f32_e32 v227, v247, v21
	v_fma_f32 v236, v246, v20, -v227
	v_mul_f32_e32 v227, v247, v20
	v_fma_f32 v237, v246, v21, v227
	ds_write_b64 v223, v[236:237] offset:28672
	s_waitcnt lgkmcnt(4)
	v_add_f32_e32 v22, v8, v12
	v_sub_f32_e32 v24, v8, v12
	v_add_f32_e32 v26, v10, v14
	v_sub_f32_e32 v28, v10, v14
	v_add_f32_e32 v23, v9, v13
	v_sub_f32_e32 v25, v9, v13
	v_add_f32_e32 v27, v11, v15
	v_sub_f32_e32 v29, v11, v15
	v_add_f32_e32 v80, v22, v26
	v_add_f32_e32 v81, v23, v27
	ds_write_b64 v223, v[80:81] offset:36864
	v_sub_f32_e32 v242, v22, v26
	v_sub_f32_e32 v243, v23, v27
	v_add_f32_e32 v244, v24, v29
	v_sub_f32_e32 v245, v25, v28
	v_sub_f32_e32 v246, v24, v29
	v_add_f32_e32 v247, v25, v28
	v_mul_f32_e32 v227, v245, v17
	v_fma_f32 v82, v244, v16, -v227
	v_mul_f32_e32 v227, v245, v16
	v_fma_f32 v83, v244, v17, v227
	ds_write_b64 v223, v[82:83] offset:45056
	v_mul_f32_e32 v227, v243, v19
	v_fma_f32 v84, v242, v18, -v227
	v_mul_f32_e32 v227, v243, v18
	v_fma_f32 v85, v242, v19, v227
	ds_write_b64 v223, v[84:85] offset:53248
	v_mul_f32_e32 v227, v247, v21
	v_fma_f32 v236, v246, v20, -v227
	v_mul_f32_e32 v227, v247, v20
	v_fma_f32 v237, v246, v21, v227
	ds_write_b64 v223, v[236:237] offset:61440
	s_waitcnt lgkmcnt(0)
	s_barrier
; HD float2 cmul(float2 a, float2 b){ return make_float2(a.x*b.x - a.y*b.y, a.x*b.y + a.y*b.x); }
; HD float2 cmulc(float2 a, float2 b){ return make_float2(a.x*b.x + a.y*b.y, a.y*b.x - a.x*b.y); }
; template<bool INV, bool NOTW>
; HD void bf4c(float2* Z, int i0, int i1, int i2, int i3, float2 w1, float2 w2, float2 w3){
;   float2 a0=Z[i0], a1=Z[i1], a2=Z[i2], a3=Z[i3];
;   if (INV && !NOTW){ a1=cmulc(a1,w1); a2=cmulc(a2,w2); a3=cmulc(a3,w3); }
;   float2 s02=make_float2(a0.x+a2.x,a0.y+a2.y), d02=make_float2(a0.x-a2.x,a0.y-a2.y);
;   float2 s13=make_float2(a1.x+a3.x,a1.y+a3.y), d13=make_float2(a1.x-a3.x,a1.y-a3.y);
;   float2 y0=make_float2(s02.x+s13.x,s02.y+s13.y), y2=make_float2(s02.x-s13.x,s02.y-s13.y);
;   float2 ym=make_float2(d02.x+d13.y,d02.y-d13.x);
;   float2 yp=make_float2(d02.x-d13.y,d02.y+d13.x);
;   float2 y1, y3;
;   if (INV){ y1=yp; y3=ym; } else if (NOTW){ y1=ym; y3=yp; } else { y1=cmul(ym,w1); y2=cmul(y2,w2); y3=cmul(yp,w3); }
;   Z[i0]=y0; Z[i1]=y1; Z[i2]=y2; Z[i3]=y3;
; }
; template<bool INV, int LQ, bool BARRIER=true>
; HD void fft_pass(float2* Z, const float2* twA, const float2* twB, int tid){
;     ...
;   } else {
;     int j=tid&(q-1); int base0=((tid>>LQ)<<(LQ+2))+j;
;     float2 w1=make_float2(1.f,0.f), w2=w1, w3=w1;
;     if (LQ>0){ int k=j*tws; w1=cmul(twA[k>>6],twB[k&63]); w2=cmul(w1,w1); w3=cmul(w2,w1); }
;     _Pragma("unroll") for (int i=0;i<8;++i){ int base=base0+i*2048; bf4c<INV,(LQ==0)>(Z,base,base+q,base+2*q,base+3*q,w1,w2,w3); }
;   }
;   if (BARRIER) __syncthreads(); else asm volatile("s_waitcnt lgkmcnt(0)" ::: "memory");
	v_and_b32_e32 v226, 255, v154
	v_lshrrev_b32_e32 v224, 2, v226
	v_lshlrev_b32_e32 v224, 3, v224
	v_add_u32_e32 v224, 0x20800, v224
	v_and_b32_e32 v225, 3, v226
	v_lshlrev_b32_e32 v225, 7, v225
	v_add_u32_e32 v225, 0x20a00, v225
	ds_read_b64 v[238:239], v224
	ds_read_b64 v[240:241], v225
	s_waitcnt lgkmcnt(0)
	v_mul_f32_e32 v227, v239, v241
	v_fma_f32 v16, v238, v240, -v227
	v_mul_f32_e32 v227, v239, v240
	v_fma_f32 v17, v238, v241, v227
	v_mul_f32_e32 v227, v17, v17
	v_fma_f32 v18, v16, v16, -v227
	v_mul_f32_e32 v227, v17, v16
	v_fma_f32 v19, v16, v17, v227
	v_mul_f32_e32 v227, v19, v17
	v_fma_f32 v20, v18, v16, -v227
	v_mul_f32_e32 v227, v19, v16
	v_fma_f32 v21, v18, v17, v227
	v_lshrrev_b32_e32 v222, 8, v154
	v_lshlrev_b32_e32 v222, 10, v222
	v_add_u32_e32 v222, v222, v226
	v_lshlrev_b32_e32 v222, 3, v222
	v_add_u32_e32 v223, 0x10000, v222
	ds_read_b64 v[0:1], v222 offset:0
	ds_read_b64 v[2:3], v222 offset:2048
	ds_read_b64 v[4:5], v222 offset:4096
	ds_read_b64 v[6:7], v222 offset:6144
	ds_read_b64 v[8:9], v222 offset:16384
	ds_read_b64 v[10:11], v222 offset:18432
	ds_read_b64 v[12:13], v222 offset:20480
	ds_read_b64 v[14:15], v222 offset:22528
	s_waitcnt lgkmcnt(4)
	v_add_f32_e32 v22, v0, v4
	v_sub_f32_e32 v24, v0, v4
	v_add_f32_e32 v26, v2, v6
	v_sub_f32_e32 v28, v2, v6
	v_add_f32_e32 v23, v1, v5
	v_sub_f32_e32 v25, v1, v5
	v_add_f32_e32 v27, v3, v7
	v_sub_f32_e32 v29, v3, v7
	v_add_f32_e32 v80, v22, v26
	v_add_f32_e32 v81, v23, v27
	ds_write_b64 v222, v[80:81] offset:0
	v_sub_f32_e32 v242, v22, v26
	v_sub_f32_e32 v243, v23, v27
	v_add_f32_e32 v244, v24, v29
	v_sub_f32_e32 v245, v25, v28
	v_sub_f32_e32 v246, v24, v29
	v_add_f32_e32 v247, v25, v28
	v_mul_f32_e32 v227, v245, v17
	v_fma_f32 v82, v244, v16, -v227
	v_mul_f32_e32 v227, v245, v16
	v_fma_f32 v83, v244, v17, v227
	ds_write_b64 v222, v[82:83] offset:2048
	v_mul_f32_e32 v227, v243, v19
	v_fma_f32 v84, v242, v18, -v227
	v_mul_f32_e32 v227, v243, v18
	v_fma_f32 v85, v242, v19, v227
	ds_write_b64 v222, v[84:85] offset:4096
	v_mul_f32_e32 v227, v247, v21
	v_fma_f32 v236, v246, v20, -v227
	v_mul_f32_e32 v227, v247, v20
	v_fma_f32 v237, v246, v21, v227
	ds_write_b64 v222, v[236:237] offset:6144
	ds_read_b64 v[0:1], v222 offset:32768
	ds_read_b64 v[2:3], v222 offset:34816
	ds_read_b64 v[4:5], v222 offset:36864
	ds_read_b64 v[6:7], v222 offset:38912
	s_waitcnt lgkmcnt(8)
	v_add_f32_e32 v22, v8, v12
	v_sub_f32_e32 v24, v8, v12
	v_add_f32_e32 v26, v10, v14
	v_sub_f32_e32 v28, v10, v14
	v_add_f32_e32 v23, v9, v13
	v_sub_f32_e32 v25, v9, v13
	v_add_f32_e32 v27, v11, v15
	v_sub_f32_e32 v29, v11, v15
	v_add_f32_e32 v80, v22, v26
	v_add_f32_e32 v81, v23, v27
	ds_write_b64 v222, v[80:81] offset:16384
	v_sub_f32_e32 v242, v22, v26
	v_sub_f32_e32 v243, v23, v27
	v_add_f32_e32 v244, v24, v29
	v_sub_f32_e32 v245, v25, v28
	v_sub_f32_e32 v246, v24, v29
	v_add_f32_e32 v247, v25, v28
	v_mul_f32_e32 v227, v245, v17
	v_fma_f32 v82, v244, v16, -v227
	v_mul_f32_e32 v227, v245, v16
	v_fma_f32 v83, v244, v17, v227
	ds_write_b64 v222, v[82:83] offset:18432
	v_mul_f32_e32 v227, v243, v19
	v_fma_f32 v84, v242, v18, -v227
	v_mul_f32_e32 v227, v243, v18
	v_fma_f32 v85, v242, v19, v227
	ds_write_b64 v222, v[84:85] offset:20480
	v_mul_f32_e32 v227, v247, v21
	v_fma_f32 v236, v246, v20, -v227
	v_mul_f32_e32 v227, v247, v20
	v_fma_f32 v237, v246, v21, v227
	ds_write_b64 v222, v[236:237] offset:22528
	ds_read_b64 v[8:9], v222 offset:49152
	ds_read_b64 v[10:11], v222 offset:51200
	ds_read_b64 v[12:13], v222 offset:53248
	ds_read_b64 v[14:15], v222 offset:55296
	s_waitcnt lgkmcnt(8)
	v_add_f32_e32 v22, v0, v4
	v_sub_f32_e32 v24, v0, v4
	v_add_f32_e32 v26, v2, v6
	v_sub_f32_e32 v28, v2, v6
	v_add_f32_e32 v23, v1, v5
	v_sub_f32_e32 v25, v1, v5
	v_add_f32_e32 v27, v3, v7
	v_sub_f32_e32 v29, v3, v7
	v_add_f32_e32 v80, v22, v26
	v_add_f32_e32 v81, v23, v27
	ds_write_b64 v222, v[80:81] offset:32768
	v_sub_f32_e32 v242, v22, v26
	v_sub_f32_e32 v243, v23, v27
	v_add_f32_e32 v244, v24, v29
	v_sub_f32_e32 v245, v25, v28
	v_sub_f32_e32 v246, v24, v29
	v_add_f32_e32 v247, v25, v28
	v_mul_f32_e32 v227, v245, v17
	v_fma_f32 v82, v244, v16, -v227
	v_mul_f32_e32 v227, v245, v16
	v_fma_f32 v83, v244, v17, v227
	ds_write_b64 v222, v[82:83] offset:34816
	v_mul_f32_e32 v227, v243, v19
	v_fma_f32 v84, v242, v18, -v227
	v_mul_f32_e32 v227, v243, v18
	v_fma_f32 v85, v242, v19, v227
	ds_write_b64 v222, v[84:85] offset:36864
	v_mul_f32_e32 v227, v247, v21
	v_fma_f32 v236, v246, v20, -v227
	v_mul_f32_e32 v227, v247, v20
	v_fma_f32 v237, v246, v21, v227
	ds_write_b64 v222, v[236:237] offset:38912
	ds_read_b64 v[0:1], v223 offset:0
	ds_read_b64 v[2:3], v223 offset:2048
	ds_read_b64 v[4:5], v223 offset:4096
	ds_read_b64 v[6:7], v223 offset:6144
	s_waitcnt lgkmcnt(8)
	v_add_f32_e32 v22, v8, v12
	v_sub_f32_e32 v24, v8, v12
	v_add_f32_e32 v26, v10, v14
	v_sub_f32_e32 v28, v10, v14
	v_add_f32_e32 v23, v9, v13
	v_sub_f32_e32 v25, v9, v13
	v_add_f32_e32 v27, v11, v15
	v_sub_f32_e32 v29, v11, v15
	v_add_f32_e32 v80, v22, v26
	v_add_f32_e32 v81, v23, v27
	ds_write_b64 v222, v[80:81] offset:49152
	v_sub_f32_e32 v242, v22, v26
	v_sub_f32_e32 v243, v23, v27
	v_add_f32_e32 v244, v24, v29
	v_sub_f32_e32 v245, v25, v28
	v_sub_f32_e32 v246, v24, v29
	v_add_f32_e32 v247, v25, v28
	v_mul_f32_e32 v227, v245, v17
	v_fma_f32 v82, v244, v16, -v227
	v_mul_f32_e32 v227, v245, v16
	v_fma_f32 v83, v244, v17, v227
	ds_write_b64 v222, v[82:83] offset:51200
	v_mul_f32_e32 v227, v243, v19
	v_fma_f32 v84, v242, v18, -v227
	v_mul_f32_e32 v227, v243, v18
	v_fma_f32 v85, v242, v19, v227
	ds_write_b64 v222, v[84:85] offset:53248
	v_mul_f32_e32 v227, v247, v21
	v_fma_f32 v236, v246, v20, -v227
	v_mul_f32_e32 v227, v247, v20
	v_fma_f32 v237, v246, v21, v227
	ds_write_b64 v222, v[236:237] offset:55296
	ds_read_b64 v[8:9], v223 offset:16384
	ds_read_b64 v[10:11], v223 offset:18432
	ds_read_b64 v[12:13], v223 offset:20480
	ds_read_b64 v[14:15], v223 offset:22528
	s_waitcnt lgkmcnt(8)
; HD float2 cmul(float2 a, float2 b){ return make_float2(a.x*b.x - a.y*b.y, a.x*b.y + a.y*b.x); }
; HD float2 cmulc(float2 a, float2 b){ return make_float2(a.x*b.x + a.y*b.y, a.y*b.x - a.x*b.y); }
; template<bool INV, bool NOTW>
; HD void bf4c(float2* Z, int i0, int i1, int i2, int i3, float2 w1, float2 w2, float2 w3){
;   float2 a0=Z[i0], a1=Z[i1], a2=Z[i2], a3=Z[i3];
;   if (INV && !NOTW){ a1=cmulc(a1,w1); a2=cmulc(a2,w2); a3=cmulc(a3,w3); }
;   float2 s02=make_float2(a0.x+a2.x,a0.y+a2.y), d02=make_float2(a0.x-a2.x,a0.y-a2.y);
;   float2 s13=make_float2(a1.x+a3.x,a1.y+a3.y), d13=make_float2(a1.x-a3.x,a1.y-a3.y);
;   float2 y0=make_float2(s02.x+s13.x,s02.y+s13.y), y2=make_float2(s02.x-s13.x,s02.y-s13.y);
;   float2 ym=make_float2(d02.x+d13.y,d02.y-d13.x);
;   float2 yp=make_float2(d02.x-d13.y,d02.y+d13.x);
;   float2 y1, y3;
;   if (INV){ y1=yp; y3=ym; } else if (NOTW){ y1=ym; y3=yp; } else { y1=cmul(ym,w1); y2=cmul(y2,w2); y3=cmul(yp,w3); }
;   Z[i0]=y0; Z[i1]=y1; Z[i2]=y2; Z[i3]=y3;
; }
; template<bool INV, int LQ, bool BARRIER=true>
; HD void fft_pass(float2* Z, const float2* twA, const float2* twB, int tid){
;     ...
;   } else {
;     int j=tid&(q-1); int base0=((tid>>LQ)<<(LQ+2))+j;
;     float2 w1=make_float2(1.f,0.f), w2=w1, w3=w1;
;     if (LQ>0){ int k=j*tws; w1=cmul(twA[k>>6],twB[k&63]); w2=cmul(w1,w1); w3=cmul(w2,w1); }
;     _Pragma("unroll") for (int i=0;i<8;++i){ int base=base0+i*2048; bf4c<INV,(LQ==0)>(Z,base,base+q,base+2*q,base+3*q,w1,w2,w3); }
;   }
;   if (BARRIER) __syncthreads(); else asm volatile("s_waitcnt lgkmcnt(0)" ::: "memory");
	v_add_f32_e32 v22, v0, v4
	v_sub_f32_e32 v24, v0, v4
	v_add_f32_e32 v26, v2, v6
	v_sub_f32_e32 v28, v2, v6
	v_add_f32_e32 v23, v1, v5
	v_sub_f32_e32 v25, v1, v5
	v_add_f32_e32 v27, v3, v7
	v_sub_f32_e32 v29, v3, v7
	v_add_f32_e32 v80, v22, v26
	v_add_f32_e32 v81, v23, v27
	ds_write_b64 v223, v[80:81] offset:0
	v_sub_f32_e32 v242, v22, v26
	v_sub_f32_e32 v243, v23, v27
	v_add_f32_e32 v244, v24, v29
	v_sub_f32_e32 v245, v25, v28
	v_sub_f32_e32 v246, v24, v29
	v_add_f32_e32 v247, v25, v28
	v_mul_f32_e32 v227, v245, v17
	v_fma_f32 v82, v244, v16, -v227
	v_mul_f32_e32 v227, v245, v16
	v_fma_f32 v83, v244, v17, v227
	ds_write_b64 v223, v[82:83] offset:2048
	v_mul_f32_e32 v227, v243, v19
	v_fma_f32 v84, v242, v18, -v227
	v_mul_f32_e32 v227, v243, v18
	v_fma_f32 v85, v242, v19, v227
	ds_write_b64 v223, v[84:85] offset:4096
	v_mul_f32_e32 v227, v247, v21
	v_fma_f32 v236, v246, v20, -v227
	v_mul_f32_e32 v227, v247, v20
	v_fma_f32 v237, v246, v21, v227
	ds_write_b64 v223, v[236:237] offset:6144
	ds_read_b64 v[0:1], v223 offset:32768
	ds_read_b64 v[2:3], v223 offset:34816
	ds_read_b64 v[4:5], v223 offset:36864
	ds_read_b64 v[6:7], v223 offset:38912
	s_waitcnt lgkmcnt(8)
	v_add_f32_e32 v22, v8, v12
	v_sub_f32_e32 v24, v8, v12
	v_add_f32_e32 v26, v10, v14
	v_sub_f32_e32 v28, v10, v14
	v_add_f32_e32 v23, v9, v13
	v_sub_f32_e32 v25, v9, v13
	v_add_f32_e32 v27, v11, v15
	v_sub_f32_e32 v29, v11, v15
	v_add_f32_e32 v80, v22, v26
	v_add_f32_e32 v81, v23, v27
	ds_write_b64 v223, v[80:81] offset:16384
	v_sub_f32_e32 v242, v22, v26
	v_sub_f32_e32 v243, v23, v27
	v_add_f32_e32 v244, v24, v29
	v_sub_f32_e32 v245, v25, v28
	v_sub_f32_e32 v246, v24, v29
	v_add_f32_e32 v247, v25, v28
	v_mul_f32_e32 v227, v245, v17
	v_fma_f32 v82, v244, v16, -v227
	v_mul_f32_e32 v227, v245, v16
	v_fma_f32 v83, v244, v17, v227
	ds_write_b64 v223, v[82:83] offset:18432
	v_mul_f32_e32 v227, v243, v19
	v_fma_f32 v84, v242, v18, -v227
	v_mul_f32_e32 v227, v243, v18
	v_fma_f32 v85, v242, v19, v227
	ds_write_b64 v223, v[84:85] offset:20480
	v_mul_f32_e32 v227, v247, v21
	v_fma_f32 v236, v246, v20, -v227
	v_mul_f32_e32 v227, v247, v20
	v_fma_f32 v237, v246, v21, v227
	ds_write_b64 v223, v[236:237] offset:22528
	ds_read_b64 v[8:9], v223 offset:49152
	ds_read_b64 v[10:11], v223 offset:51200
	ds_read_b64 v[12:13], v223 offset:53248
	ds_read_b64 v[14:15], v223 offset:55296
	s_waitcnt lgkmcnt(8)
	v_add_f32_e32 v22, v0, v4
	v_sub_f32_e32 v24, v0, v4
	v_add_f32_e32 v26, v2, v6
	v_sub_f32_e32 v28, v2, v6
	v_add_f32_e32 v23, v1, v5
	v_sub_f32_e32 v25, v1, v5
	v_add_f32_e32 v27, v3, v7
	v_sub_f32_e32 v29, v3, v7
	v_add_f32_e32 v80, v22, v26
	v_add_f32_e32 v81, v23, v27
	ds_write_b64 v223, v[80:81] offset:32768
	v_sub_f32_e32 v242, v22, v26
	v_sub_f32_e32 v243, v23, v27
	v_add_f32_e32 v244, v24, v29
	v_sub_f32_e32 v245, v25, v28
	v_sub_f32_e32 v246, v24, v29
	v_add_f32_e32 v247, v25, v28
	v_mul_f32_e32 v227, v245, v17
	v_fma_f32 v82, v244, v16, -v227
	v_mul_f32_e32 v227, v245, v16
	v_fma_f32 v83, v244, v17, v227
	ds_write_b64 v223, v[82:83] offset:34816
	v_mul_f32_e32 v227, v243, v19
	v_fma_f32 v84, v242, v18, -v227
	v_mul_f32_e32 v227, v243, v18
	v_fma_f32 v85, v242, v19, v227
	ds_write_b64 v223, v[84:85] offset:36864
	v_mul_f32_e32 v227, v247, v21
	v_fma_f32 v236, v246, v20, -v227
	v_mul_f32_e32 v227, v247, v20
	v_fma_f32 v237, v246, v21, v227
	ds_write_b64 v223, v[236:237] offset:38912
	s_waitcnt lgkmcnt(4)
	v_add_f32_e32 v22, v8, v12
	v_sub_f32_e32 v24, v8, v12
	v_add_f32_e32 v26, v10, v14
	v_sub_f32_e32 v28, v10, v14
	v_add_f32_e32 v23, v9, v13
	v_sub_f32_e32 v25, v9, v13
	v_add_f32_e32 v27, v11, v15
	v_sub_f32_e32 v29, v11, v15
	v_add_f32_e32 v80, v22, v26
	v_add_f32_e32 v81, v23, v27
	ds_write_b64 v223, v[80:81] offset:49152
	v_sub_f32_e32 v242, v22, v26
	v_sub_f32_e32 v243, v23, v27
	v_add_f32_e32 v244, v24, v29
	v_sub_f32_e32 v245, v25, v28
	v_sub_f32_e32 v246, v24, v29
	v_add_f32_e32 v247, v25, v28
	v_mul_f32_e32 v227, v245, v17
	v_fma_f32 v82, v244, v16, -v227
	v_mul_f32_e32 v227, v245, v16
	v_fma_f32 v83, v244, v17, v227
	ds_write_b64 v223, v[82:83] offset:51200
	v_mul_f32_e32 v227, v243, v19
	v_fma_f32 v84, v242, v18, -v227
	v_mul_f32_e32 v227, v243, v18
	v_fma_f32 v85, v242, v19, v227
	ds_write_b64 v223, v[84:85] offset:53248
	v_mul_f32_e32 v227, v247, v21
	v_fma_f32 v236, v246, v20, -v227
	v_mul_f32_e32 v227, v247, v20
	v_fma_f32 v237, v246, v21, v227
	ds_write_b64 v223, v[236:237] offset:55296
	s_waitcnt lgkmcnt(0)
	s_barrier
; HD float2 cmul(float2 a, float2 b){ return make_float2(a.x*b.x - a.y*b.y, a.x*b.y + a.y*b.x); }
; HD float2 cmulc(float2 a, float2 b){ return make_float2(a.x*b.x + a.y*b.y, a.y*b.x - a.x*b.y); }
; template<bool INV, bool NOTW>
; HD void bf4c(float2* Z, int i0, int i1, int i2, int i3, float2 w1, float2 w2, float2 w3){
;   float2 a0=Z[i0], a1=Z[i1], a2=Z[i2], a3=Z[i3];
;   if (INV && !NOTW){ a1=cmulc(a1,w1); a2=cmulc(a2,w2); a3=cmulc(a3,w3); }
;   float2 s02=make_float2(a0.x+a2.x,a0.y+a2.y), d02=make_float2(a0.x-a2.x,a0.y-a2.y);
;   float2 s13=make_float2(a1.x+a3.x,a1.y+a3.y), d13=make_float2(a1.x-a3.x,a1.y-a3.y);
;   float2 y0=make_float2(s02.x+s13.x,s02.y+s13.y), y2=make_float2(s02.x-s13.x,s02.y-s13.y);
;   float2 ym=make_float2(d02.x+d13.y,d02.y-d13.x);
;   float2 yp=make_float2(d02.x-d13.y,d02.y+d13.x);
;   float2 y1, y3;
;   if (INV){ y1=yp; y3=ym; } else if (NOTW){ y1=ym; y3=yp; } else { y1=cmul(ym,w1); y2=cmul(y2,w2); y3=cmul(yp,w3); }
;   Z[i0]=y0; Z[i1]=y1; Z[i2]=y2; Z[i3]=y3;
; }
; template<bool INV, int LQ, bool BARRIER=true>
; HD void fft_pass(float2* Z, const float2* twA, const float2* twB, int tid){
;     ...
;   } else {
;     int j=tid&(q-1); int base0=((tid>>LQ)<<(LQ+2))+j;
;     float2 w1=make_float2(1.f,0.f), w2=w1, w3=w1;
;     if (LQ>0){ int k=j*tws; w1=cmul(twA[k>>6],twB[k&63]); w2=cmul(w1,w1); w3=cmul(w2,w1); }
;     _Pragma("unroll") for (int i=0;i<8;++i){ int base=base0+i*2048; bf4c<INV,(LQ==0)>(Z,base,base+q,base+2*q,base+3*q,w1,w2,w3); }
;   }
;   if (BARRIER) __syncthreads(); else asm volatile("s_waitcnt lgkmcnt(0)" ::: "memory");
	v_and_b32_e32 v226, 63, v154
	v_lshlrev_b32_e32 v224, 3, v226
	v_add_u32_e32 v224, 0x20800, v224
	v_mov_b32_e32 v225, 0x20a00
	ds_read_b64 v[238:239], v224
	ds_read_b64 v[240:241], v225
	s_waitcnt lgkmcnt(0)
	v_mul_f32_e32 v227, v239, v241
	v_fma_f32 v16, v238, v240, -v227
	v_mul_f32_e32 v227, v239, v240
	v_fma_f32 v17, v238, v241, v227
	v_mul_f32_e32 v227, v17, v17
	v_fma_f32 v18, v16, v16, -v227
	v_mul_f32_e32 v227, v17, v16
	v_fma_f32 v19, v16, v17, v227
	v_mul_f32_e32 v227, v19, v17
	v_fma_f32 v20, v18, v16, -v227
	v_mul_f32_e32 v227, v19, v16
	v_fma_f32 v21, v18, v17, v227
	v_lshrrev_b32_e32 v222, 6, v154
	v_lshlrev_b32_e32 v222, 8, v222
	v_add_u32_e32 v222, v222, v226
	v_lshlrev_b32_e32 v222, 3, v222
	v_add_u32_e32 v223, 0x10000, v222
	ds_read_b64 v[0:1], v222 offset:0
	ds_read_b64 v[2:3], v222 offset:512
	ds_read_b64 v[4:5], v222 offset:1024
	ds_read_b64 v[6:7], v222 offset:1536
	ds_read_b64 v[8:9], v222 offset:16384
	ds_read_b64 v[10:11], v222 offset:16896
	ds_read_b64 v[12:13], v222 offset:17408
	ds_read_b64 v[14:15], v222 offset:17920
	s_waitcnt lgkmcnt(4)
	v_add_f32_e32 v22, v0, v4
	v_sub_f32_e32 v24, v0, v4
	v_add_f32_e32 v26, v2, v6
	v_sub_f32_e32 v28, v2, v6
	v_add_f32_e32 v23, v1, v5
	v_sub_f32_e32 v25, v1, v5
	v_add_f32_e32 v27, v3, v7
	v_sub_f32_e32 v29, v3, v7
	v_add_f32_e32 v80, v22, v26
	v_add_f32_e32 v81, v23, v27
	ds_write_b64 v222, v[80:81] offset:0
	v_sub_f32_e32 v242, v22, v26
	v_sub_f32_e32 v243, v23, v27
	v_add_f32_e32 v244, v24, v29
	v_sub_f32_e32 v245, v25, v28
	v_sub_f32_e32 v246, v24, v29
	v_add_f32_e32 v247, v25, v28
	v_mul_f32_e32 v227, v245, v17
	v_fma_f32 v82, v244, v16, -v227
	v_mul_f32_e32 v227, v245, v16
	v_fma_f32 v83, v244, v17, v227
	ds_write_b64 v222, v[82:83] offset:512
	v_mul_f32_e32 v227, v243, v19
	v_fma_f32 v84, v242, v18, -v227
	v_mul_f32_e32 v227, v243, v18
	v_fma_f32 v85, v242, v19, v227
	ds_write_b64 v222, v[84:85] offset:1024
	v_mul_f32_e32 v227, v247, v21
	v_fma_f32 v236, v246, v20, -v227
	v_mul_f32_e32 v227, v247, v20
	v_fma_f32 v237, v246, v21, v227
	ds_write_b64 v222, v[236:237] offset:1536
	ds_read_b64 v[0:1], v222 offset:32768
	ds_read_b64 v[2:3], v222 offset:33280
	ds_read_b64 v[4:5], v222 offset:33792
	ds_read_b64 v[6:7], v222 offset:34304
	s_waitcnt lgkmcnt(8)
	v_add_f32_e32 v22, v8, v12
	v_sub_f32_e32 v24, v8, v12
	v_add_f32_e32 v26, v10, v14
	v_sub_f32_e32 v28, v10, v14
	v_add_f32_e32 v23, v9, v13
	v_sub_f32_e32 v25, v9, v13
	v_add_f32_e32 v27, v11, v15
	v_sub_f32_e32 v29, v11, v15
	v_add_f32_e32 v80, v22, v26
	v_add_f32_e32 v81, v23, v27
	ds_write_b64 v222, v[80:81] offset:16384
	v_sub_f32_e32 v242, v22, v26
	v_sub_f32_e32 v243, v23, v27
	v_add_f32_e32 v244, v24, v29
	v_sub_f32_e32 v245, v25, v28
	v_sub_f32_e32 v246, v24, v29
	v_add_f32_e32 v247, v25, v28
	v_mul_f32_e32 v227, v245, v17
	v_fma_f32 v82, v244, v16, -v227
	v_mul_f32_e32 v227, v245, v16
	v_fma_f32 v83, v244, v17, v227
	ds_write_b64 v222, v[82:83] offset:16896
	v_mul_f32_e32 v227, v243, v19
	v_fma_f32 v84, v242, v18, -v227
	v_mul_f32_e32 v227, v243, v18
	v_fma_f32 v85, v242, v19, v227
	ds_write_b64 v222, v[84:85] offset:17408
	v_mul_f32_e32 v227, v247, v21
	v_fma_f32 v236, v246, v20, -v227
	v_mul_f32_e32 v227, v247, v20
	v_fma_f32 v237, v246, v21, v227
	ds_write_b64 v222, v[236:237] offset:17920
	ds_read_b64 v[8:9], v222 offset:49152
	ds_read_b64 v[10:11], v222 offset:49664
	ds_read_b64 v[12:13], v222 offset:50176
	ds_read_b64 v[14:15], v222 offset:50688
	s_waitcnt lgkmcnt(8)
	v_add_f32_e32 v22, v0, v4
	v_sub_f32_e32 v24, v0, v4
	v_add_f32_e32 v26, v2, v6
	v_sub_f32_e32 v28, v2, v6
	v_add_f32_e32 v23, v1, v5
	v_sub_f32_e32 v25, v1, v5
	v_add_f32_e32 v27, v3, v7
	v_sub_f32_e32 v29, v3, v7
	v_add_f32_e32 v80, v22, v26
	v_add_f32_e32 v81, v23, v27
	ds_write_b64 v222, v[80:81] offset:32768
	v_sub_f32_e32 v242, v22, v26
	v_sub_f32_e32 v243, v23, v27
	v_add_f32_e32 v244, v24, v29
	v_sub_f32_e32 v245, v25, v28
	v_sub_f32_e32 v246, v24, v29
	v_add_f32_e32 v247, v25, v28
	v_mul_f32_e32 v227, v245, v17
	v_fma_f32 v82, v244, v16, -v227
	v_mul_f32_e32 v227, v245, v16
	v_fma_f32 v83, v244, v17, v227
	ds_write_b64 v222, v[82:83] offset:33280
	v_mul_f32_e32 v227, v243, v19
	v_fma_f32 v84, v242, v18, -v227
	v_mul_f32_e32 v227, v243, v18
	v_fma_f32 v85, v242, v19, v227
	ds_write_b64 v222, v[84:85] offset:33792
	v_mul_f32_e32 v227, v247, v21
	v_fma_f32 v236, v246, v20, -v227
	v_mul_f32_e32 v227, v247, v20
	v_fma_f32 v237, v246, v21, v227
	ds_write_b64 v222, v[236:237] offset:34304
	ds_read_b64 v[0:1], v223 offset:0
	ds_read_b64 v[2:3], v223 offset:512
	ds_read_b64 v[4:5], v223 offset:1024
	ds_read_b64 v[6:7], v223 offset:1536
	s_waitcnt lgkmcnt(8)
	v_add_f32_e32 v22, v8, v12
	v_sub_f32_e32 v24, v8, v12
	v_add_f32_e32 v26, v10, v14
	v_sub_f32_e32 v28, v10, v14
	v_add_f32_e32 v23, v9, v13
	v_sub_f32_e32 v25, v9, v13
	v_add_f32_e32 v27, v11, v15
	v_sub_f32_e32 v29, v11, v15
	v_add_f32_e32 v80, v22, v26
	v_add_f32_e32 v81, v23, v27
	ds_write_b64 v222, v[80:81] offset:49152
	v_sub_f32_e32 v242, v22, v26
	v_sub_f32_e32 v243, v23, v27
	v_add_f32_e32 v244, v24, v29
	v_sub_f32_e32 v245, v25, v28
	v_sub_f32_e32 v246, v24, v29
	v_add_f32_e32 v247, v25, v28
	v_mul_f32_e32 v227, v245, v17
	v_fma_f32 v82, v244, v16, -v227
	v_mul_f32_e32 v227, v245, v16
	v_fma_f32 v83, v244, v17, v227
	ds_write_b64 v222, v[82:83] offset:49664
	v_mul_f32_e32 v227, v243, v19
	v_fma_f32 v84, v242, v18, -v227
	v_mul_f32_e32 v227, v243, v18
	v_fma_f32 v85, v242, v19, v227
	ds_write_b64 v222, v[84:85] offset:50176
	v_mul_f32_e32 v227, v247, v21
	v_fma_f32 v236, v246, v20, -v227
	v_mul_f32_e32 v227, v247, v20
	v_fma_f32 v237, v246, v21, v227
	ds_write_b64 v222, v[236:237] offset:50688
	ds_read_b64 v[8:9], v223 offset:16384
	ds_read_b64 v[10:11], v223 offset:16896
	ds_read_b64 v[12:13], v223 offset:17408
	ds_read_b64 v[14:15], v223 offset:17920
	s_waitcnt lgkmcnt(8)
; HD float2 cmul(float2 a, float2 b){ return make_float2(a.x*b.x - a.y*b.y, a.x*b.y + a.y*b.x); }
; HD float2 cmulc(float2 a, float2 b){ return make_float2(a.x*b.x + a.y*b.y, a.y*b.x - a.x*b.y); }
; template<bool INV, bool NOTW>
; HD void bf4c(float2* Z, int i0, int i1, int i2, int i3, float2 w1, float2 w2, float2 w3){
;   float2 a0=Z[i0], a1=Z[i1], a2=Z[i2], a3=Z[i3];
;   if (INV && !NOTW){ a1=cmulc(a1,w1); a2=cmulc(a2,w2); a3=cmulc(a3,w3); }
;   float2 s02=make_float2(a0.x+a2.x,a0.y+a2.y), d02=make_float2(a0.x-a2.x,a0.y-a2.y);
;   float2 s13=make_float2(a1.x+a3.x,a1.y+a3.y), d13=make_float2(a1.x-a3.x,a1.y-a3.y);
;   float2 y0=make_float2(s02.x+s13.x,s02.y+s13.y), y2=make_float2(s02.x-s13.x,s02.y-s13.y);
;   float2 ym=make_float2(d02.x+d13.y,d02.y-d13.x);
;   float2 yp=make_float2(d02.x-d13.y,d02.y+d13.x);
;   float2 y1, y3;
;   if (INV){ y1=yp; y3=ym; } else if (NOTW){ y1=ym; y3=yp; } else { y1=cmul(ym,w1); y2=cmul(y2,w2); y3=cmul(yp,w3); }
;   Z[i0]=y0; Z[i1]=y1; Z[i2]=y2; Z[i3]=y3;
; }
; template<bool INV, int LQ, bool BARRIER=true>
; HD void fft_pass(float2* Z, const float2* twA, const float2* twB, int tid){
;     ...
;   } else {
;     int j=tid&(q-1); int base0=((tid>>LQ)<<(LQ+2))+j;
;     float2 w1=make_float2(1.f,0.f), w2=w1, w3=w1;
;     if (LQ>0){ int k=j*tws; w1=cmul(twA[k>>6],twB[k&63]); w2=cmul(w1,w1); w3=cmul(w2,w1); }
;     _Pragma("unroll") for (int i=0;i<8;++i){ int base=base0+i*2048; bf4c<INV,(LQ==0)>(Z,base,base+q,base+2*q,base+3*q,w1,w2,w3); }
;   }
;   if (BARRIER) __syncthreads(); else asm volatile("s_waitcnt lgkmcnt(0)" ::: "memory");
	v_add_f32_e32 v22, v0, v4
	v_sub_f32_e32 v24, v0, v4
	v_add_f32_e32 v26, v2, v6
	v_sub_f32_e32 v28, v2, v6
	v_add_f32_e32 v23, v1, v5
	v_sub_f32_e32 v25, v1, v5
	v_add_f32_e32 v27, v3, v7
	v_sub_f32_e32 v29, v3, v7
	v_add_f32_e32 v80, v22, v26
	v_add_f32_e32 v81, v23, v27
	ds_write_b64 v223, v[80:81] offset:0
	v_sub_f32_e32 v242, v22, v26
	v_sub_f32_e32 v243, v23, v27
	v_add_f32_e32 v244, v24, v29
	v_sub_f32_e32 v245, v25, v28
	v_sub_f32_e32 v246, v24, v29
	v_add_f32_e32 v247, v25, v28
	v_mul_f32_e32 v227, v245, v17
	v_fma_f32 v82, v244, v16, -v227
	v_mul_f32_e32 v227, v245, v16
	v_fma_f32 v83, v244, v17, v227
	ds_write_b64 v223, v[82:83] offset:512
	v_mul_f32_e32 v227, v243, v19
	v_fma_f32 v84, v242, v18, -v227
	v_mul_f32_e32 v227, v243, v18
	v_fma_f32 v85, v242, v19, v227
	ds_write_b64 v223, v[84:85] offset:1024
	v_mul_f32_e32 v227, v247, v21
	v_fma_f32 v236, v246, v20, -v227
	v_mul_f32_e32 v227, v247, v20
	v_fma_f32 v237, v246, v21, v227
	ds_write_b64 v223, v[236:237] offset:1536
	ds_read_b64 v[0:1], v223 offset:32768
	ds_read_b64 v[2:3], v223 offset:33280
	ds_read_b64 v[4:5], v223 offset:33792
	ds_read_b64 v[6:7], v223 offset:34304
	s_waitcnt lgkmcnt(8)
	v_add_f32_e32 v22, v8, v12
	v_sub_f32_e32 v24, v8, v12
	v_add_f32_e32 v26, v10, v14
	v_sub_f32_e32 v28, v10, v14
	v_add_f32_e32 v23, v9, v13
	v_sub_f32_e32 v25, v9, v13
	v_add_f32_e32 v27, v11, v15
	v_sub_f32_e32 v29, v11, v15
	v_add_f32_e32 v80, v22, v26
	v_add_f32_e32 v81, v23, v27
	ds_write_b64 v223, v[80:81] offset:16384
	v_sub_f32_e32 v242, v22, v26
	v_sub_f32_e32 v243, v23, v27
	v_add_f32_e32 v244, v24, v29
	v_sub_f32_e32 v245, v25, v28
	v_sub_f32_e32 v246, v24, v29
	v_add_f32_e32 v247, v25, v28
	v_mul_f32_e32 v227, v245, v17
	v_fma_f32 v82, v244, v16, -v227
	v_mul_f32_e32 v227, v245, v16
	v_fma_f32 v83, v244, v17, v227
	ds_write_b64 v223, v[82:83] offset:16896
	v_mul_f32_e32 v227, v243, v19
	v_fma_f32 v84, v242, v18, -v227
	v_mul_f32_e32 v227, v243, v18
	v_fma_f32 v85, v242, v19, v227
	ds_write_b64 v223, v[84:85] offset:17408
	v_mul_f32_e32 v227, v247, v21
	v_fma_f32 v236, v246, v20, -v227
	v_mul_f32_e32 v227, v247, v20
	v_fma_f32 v237, v246, v21, v227
	ds_write_b64 v223, v[236:237] offset:17920
	ds_read_b64 v[8:9], v223 offset:49152
	ds_read_b64 v[10:11], v223 offset:49664
	ds_read_b64 v[12:13], v223 offset:50176
	ds_read_b64 v[14:15], v223 offset:50688
	s_waitcnt lgkmcnt(8)
	v_add_f32_e32 v22, v0, v4
	v_sub_f32_e32 v24, v0, v4
	v_add_f32_e32 v26, v2, v6
	v_sub_f32_e32 v28, v2, v6
	v_add_f32_e32 v23, v1, v5
	v_sub_f32_e32 v25, v1, v5
	v_add_f32_e32 v27, v3, v7
	v_sub_f32_e32 v29, v3, v7
	v_add_f32_e32 v80, v22, v26
	v_add_f32_e32 v81, v23, v27
	ds_write_b64 v223, v[80:81] offset:32768
	v_sub_f32_e32 v242, v22, v26
	v_sub_f32_e32 v243, v23, v27
	v_add_f32_e32 v244, v24, v29
	v_sub_f32_e32 v245, v25, v28
	v_sub_f32_e32 v246, v24, v29
	v_add_f32_e32 v247, v25, v28
	v_mul_f32_e32 v227, v245, v17
	v_fma_f32 v82, v244, v16, -v227
	v_mul_f32_e32 v227, v245, v16
	v_fma_f32 v83, v244, v17, v227
	ds_write_b64 v223, v[82:83] offset:33280
	v_mul_f32_e32 v227, v243, v19
	v_fma_f32 v84, v242, v18, -v227
	v_mul_f32_e32 v227, v243, v18
	v_fma_f32 v85, v242, v19, v227
	ds_write_b64 v223, v[84:85] offset:33792
	v_mul_f32_e32 v227, v247, v21
	v_fma_f32 v236, v246, v20, -v227
	v_mul_f32_e32 v227, v247, v20
	v_fma_f32 v237, v246, v21, v227
	ds_write_b64 v223, v[236:237] offset:34304
	s_waitcnt lgkmcnt(4)
	v_add_f32_e32 v22, v8, v12
	v_sub_f32_e32 v24, v8, v12
	v_add_f32_e32 v26, v10, v14
	v_sub_f32_e32 v28, v10, v14
	v_add_f32_e32 v23, v9, v13
	v_sub_f32_e32 v25, v9, v13
	v_add_f32_e32 v27, v11, v15
	v_sub_f32_e32 v29, v11, v15
	v_add_f32_e32 v80, v22, v26
	v_add_f32_e32 v81, v23, v27
	ds_write_b64 v223, v[80:81] offset:49152
	v_sub_f32_e32 v242, v22, v26
	v_sub_f32_e32 v243, v23, v27
	v_add_f32_e32 v244, v24, v29
	v_sub_f32_e32 v245, v25, v28
	v_sub_f32_e32 v246, v24, v29
	v_add_f32_e32 v247, v25, v28
	v_mul_f32_e32 v227, v245, v17
	v_fma_f32 v82, v244, v16, -v227
	v_mul_f32_e32 v227, v245, v16
	v_fma_f32 v83, v244, v17, v227
	ds_write_b64 v223, v[82:83] offset:49664
	v_mul_f32_e32 v227, v243, v19
	v_fma_f32 v84, v242, v18, -v227
	v_mul_f32_e32 v227, v243, v18
	v_fma_f32 v85, v242, v19, v227
	ds_write_b64 v223, v[84:85] offset:50176
	v_mul_f32_e32 v227, v247, v21
	v_fma_f32 v236, v246, v20, -v227
	v_mul_f32_e32 v227, v247, v20
	v_fma_f32 v237, v246, v21, v227
	ds_write_b64 v223, v[236:237] offset:50688
	s_waitcnt lgkmcnt(0)
	v_and_b32_e32 v226, 15, v154
	v_lshlrev_b32_e32 v224, 5, v226
	v_add_u32_e32 v224, 0x20800, v224
	v_mov_b32_e32 v225, 0x20a00
	ds_read_b64 v[238:239], v224
	ds_read_b64 v[240:241], v225
	s_waitcnt lgkmcnt(0)
	v_mul_f32_e32 v227, v239, v241
	v_fma_f32 v16, v238, v240, -v227
	v_mul_f32_e32 v227, v239, v240
	v_fma_f32 v17, v238, v241, v227
	v_mul_f32_e32 v227, v17, v17
	v_fma_f32 v18, v16, v16, -v227
	v_mul_f32_e32 v227, v17, v16
	v_fma_f32 v19, v16, v17, v227
	v_mul_f32_e32 v227, v19, v17
	v_fma_f32 v20, v18, v16, -v227
	v_mul_f32_e32 v227, v19, v16
	v_fma_f32 v21, v18, v17, v227
	v_lshrrev_b32_e32 v222, 4, v154
	v_lshlrev_b32_e32 v222, 6, v222
	v_add_u32_e32 v222, v222, v226
	v_lshlrev_b32_e32 v222, 3, v222
	v_add_u32_e32 v223, 0x10000, v222
	ds_read_b64 v[0:1], v222 offset:0
	ds_read_b64 v[2:3], v222 offset:128
	ds_read_b64 v[4:5], v222 offset:256
	ds_read_b64 v[6:7], v222 offset:384
	ds_read_b64 v[8:9], v222 offset:16384
	ds_read_b64 v[10:11], v222 offset:16512
	ds_read_b64 v[12:13], v222 offset:16640
	ds_read_b64 v[14:15], v222 offset:16768
	s_waitcnt lgkmcnt(4)
; HD float2 cmul(float2 a, float2 b){ return make_float2(a.x*b.x - a.y*b.y, a.x*b.y + a.y*b.x); }
; HD float2 cmulc(float2 a, float2 b){ return make_float2(a.x*b.x + a.y*b.y, a.y*b.x - a.x*b.y); }
; template<bool INV, bool NOTW>
; HD void bf4c(float2* Z, int i0, int i1, int i2, int i3, float2 w1, float2 w2, float2 w3){
;   float2 a0=Z[i0], a1=Z[i1], a2=Z[i2], a3=Z[i3];
;   if (INV && !NOTW){ a1=cmulc(a1,w1); a2=cmulc(a2,w2); a3=cmulc(a3,w3); }
;   float2 s02=make_float2(a0.x+a2.x,a0.y+a2.y), d02=make_float2(a0.x-a2.x,a0.y-a2.y);
;   float2 s13=make_float2(a1.x+a3.x,a1.y+a3.y), d13=make_float2(a1.x-a3.x,a1.y-a3.y);
;   float2 y0=make_float2(s02.x+s13.x,s02.y+s13.y), y2=make_float2(s02.x-s13.x,s02.y-s13.y);
;   float2 ym=make_float2(d02.x+d13.y,d02.y-d13.x);
;   float2 yp=make_float2(d02.x-d13.y,d02.y+d13.x);
;   float2 y1, y3;
;   if (INV){ y1=yp; y3=ym; } else if (NOTW){ y1=ym; y3=yp; } else { y1=cmul(ym,w1); y2=cmul(y2,w2); y3=cmul(yp,w3); }
;   Z[i0]=y0; Z[i1]=y1; Z[i2]=y2; Z[i3]=y3;
; }
; template<bool INV, int LQ, bool BARRIER=true>
; HD void fft_pass(float2* Z, const float2* twA, const float2* twB, int tid){
;     ...
;   } else {
;     int j=tid&(q-1); int base0=((tid>>LQ)<<(LQ+2))+j;
;     float2 w1=make_float2(1.f,0.f), w2=w1, w3=w1;
;     if (LQ>0){ int k=j*tws; w1=cmul(twA[k>>6],twB[k&63]); w2=cmul(w1,w1); w3=cmul(w2,w1); }
;     _Pragma("unroll") for (int i=0;i<8;++i){ int base=base0+i*2048; bf4c<INV,(LQ==0)>(Z,base,base+q,base+2*q,base+3*q,w1,w2,w3); }
;   }
;   if (BARRIER) __syncthreads(); else asm volatile("s_waitcnt lgkmcnt(0)" ::: "memory");
	v_add_f32_e32 v22, v0, v4
	v_sub_f32_e32 v24, v0, v4
	v_add_f32_e32 v26, v2, v6
	v_sub_f32_e32 v28, v2, v6
	v_add_f32_e32 v23, v1, v5
	v_sub_f32_e32 v25, v1, v5
	v_add_f32_e32 v27, v3, v7
	v_sub_f32_e32 v29, v3, v7
	v_add_f32_e32 v80, v22, v26
	v_add_f32_e32 v81, v23, v27
	ds_write_b64 v222, v[80:81] offset:0
	v_sub_f32_e32 v242, v22, v26
	v_sub_f32_e32 v243, v23, v27
	v_add_f32_e32 v244, v24, v29
	v_sub_f32_e32 v245, v25, v28
	v_sub_f32_e32 v246, v24, v29
	v_add_f32_e32 v247, v25, v28
	v_mul_f32_e32 v227, v245, v17
	v_fma_f32 v82, v244, v16, -v227
	v_mul_f32_e32 v227, v245, v16
	v_fma_f32 v83, v244, v17, v227
	ds_write_b64 v222, v[82:83] offset:128
	v_mul_f32_e32 v227, v243, v19
	v_fma_f32 v84, v242, v18, -v227
	v_mul_f32_e32 v227, v243, v18
	v_fma_f32 v85, v242, v19, v227
	ds_write_b64 v222, v[84:85] offset:256
	v_mul_f32_e32 v227, v247, v21
	v_fma_f32 v236, v246, v20, -v227
	v_mul_f32_e32 v227, v247, v20
	v_fma_f32 v237, v246, v21, v227
	ds_write_b64 v222, v[236:237] offset:384
	ds_read_b64 v[0:1], v222 offset:32768
	ds_read_b64 v[2:3], v222 offset:32896
	ds_read_b64 v[4:5], v222 offset:33024
	ds_read_b64 v[6:7], v222 offset:33152
	s_waitcnt lgkmcnt(8)
	v_add_f32_e32 v22, v8, v12
	v_sub_f32_e32 v24, v8, v12
	v_add_f32_e32 v26, v10, v14
	v_sub_f32_e32 v28, v10, v14
	v_add_f32_e32 v23, v9, v13
	v_sub_f32_e32 v25, v9, v13
	v_add_f32_e32 v27, v11, v15
	v_sub_f32_e32 v29, v11, v15
	v_add_f32_e32 v80, v22, v26
	v_add_f32_e32 v81, v23, v27
	ds_write_b64 v222, v[80:81] offset:16384
	v_sub_f32_e32 v242, v22, v26
	v_sub_f32_e32 v243, v23, v27
	v_add_f32_e32 v244, v24, v29
	v_sub_f32_e32 v245, v25, v28
	v_sub_f32_e32 v246, v24, v29
	v_add_f32_e32 v247, v25, v28
	v_mul_f32_e32 v227, v245, v17
	v_fma_f32 v82, v244, v16, -v227
	v_mul_f32_e32 v227, v245, v16
	v_fma_f32 v83, v244, v17, v227
	ds_write_b64 v222, v[82:83] offset:16512
	v_mul_f32_e32 v227, v243, v19
	v_fma_f32 v84, v242, v18, -v227
	v_mul_f32_e32 v227, v243, v18
	v_fma_f32 v85, v242, v19, v227
	ds_write_b64 v222, v[84:85] offset:16640
	v_mul_f32_e32 v227, v247, v21
	v_fma_f32 v236, v246, v20, -v227
	v_mul_f32_e32 v227, v247, v20
	v_fma_f32 v237, v246, v21, v227
	ds_write_b64 v222, v[236:237] offset:16768
	ds_read_b64 v[8:9], v222 offset:49152
	ds_read_b64 v[10:11], v222 offset:49280
	ds_read_b64 v[12:13], v222 offset:49408
	ds_read_b64 v[14:15], v222 offset:49536
	s_waitcnt lgkmcnt(8)
	v_add_f32_e32 v22, v0, v4
	v_sub_f32_e32 v24, v0, v4
	v_add_f32_e32 v26, v2, v6
	v_sub_f32_e32 v28, v2, v6
	v_add_f32_e32 v23, v1, v5
	v_sub_f32_e32 v25, v1, v5
	v_add_f32_e32 v27, v3, v7
	v_sub_f32_e32 v29, v3, v7
	v_add_f32_e32 v80, v22, v26
	v_add_f32_e32 v81, v23, v27
	ds_write_b64 v222, v[80:81] offset:32768
	v_sub_f32_e32 v242, v22, v26
	v_sub_f32_e32 v243, v23, v27
	v_add_f32_e32 v244, v24, v29
	v_sub_f32_e32 v245, v25, v28
	v_sub_f32_e32 v246, v24, v29
	v_add_f32_e32 v247, v25, v28
	v_mul_f32_e32 v227, v245, v17
	v_fma_f32 v82, v244, v16, -v227
	v_mul_f32_e32 v227, v245, v16
	v_fma_f32 v83, v244, v17, v227
	ds_write_b64 v222, v[82:83] offset:32896
	v_mul_f32_e32 v227, v243, v19
	v_fma_f32 v84, v242, v18, -v227
	v_mul_f32_e32 v227, v243, v18
	v_fma_f32 v85, v242, v19, v227
	ds_write_b64 v222, v[84:85] offset:33024
	v_mul_f32_e32 v227, v247, v21
	v_fma_f32 v236, v246, v20, -v227
	v_mul_f32_e32 v227, v247, v20
	v_fma_f32 v237, v246, v21, v227
	ds_write_b64 v222, v[236:237] offset:33152
	ds_read_b64 v[0:1], v223 offset:0
	ds_read_b64 v[2:3], v223 offset:128
	ds_read_b64 v[4:5], v223 offset:256
	ds_read_b64 v[6:7], v223 offset:384
	s_waitcnt lgkmcnt(8)
	v_add_f32_e32 v22, v8, v12
	v_sub_f32_e32 v24, v8, v12
	v_add_f32_e32 v26, v10, v14
	v_sub_f32_e32 v28, v10, v14
	v_add_f32_e32 v23, v9, v13
	v_sub_f32_e32 v25, v9, v13
	v_add_f32_e32 v27, v11, v15
	v_sub_f32_e32 v29, v11, v15
	v_add_f32_e32 v80, v22, v26
	v_add_f32_e32 v81, v23, v27
	ds_write_b64 v222, v[80:81] offset:49152
	v_sub_f32_e32 v242, v22, v26
	v_sub_f32_e32 v243, v23, v27
	v_add_f32_e32 v244, v24, v29
	v_sub_f32_e32 v245, v25, v28
	v_sub_f32_e32 v246, v24, v29
	v_add_f32_e32 v247, v25, v28
	v_mul_f32_e32 v227, v245, v17
	v_fma_f32 v82, v244, v16, -v227
	v_mul_f32_e32 v227, v245, v16
	v_fma_f32 v83, v244, v17, v227
	ds_write_b64 v222, v[82:83] offset:49280
	v_mul_f32_e32 v227, v243, v19
	v_fma_f32 v84, v242, v18, -v227
	v_mul_f32_e32 v227, v243, v18
	v_fma_f32 v85, v242, v19, v227
	ds_write_b64 v222, v[84:85] offset:49408
	v_mul_f32_e32 v227, v247, v21
	v_fma_f32 v236, v246, v20, -v227
	v_mul_f32_e32 v227, v247, v20
	v_fma_f32 v237, v246, v21, v227
	ds_write_b64 v222, v[236:237] offset:49536
	ds_read_b64 v[8:9], v223 offset:16384
	ds_read_b64 v[10:11], v223 offset:16512
	ds_read_b64 v[12:13], v223 offset:16640
	ds_read_b64 v[14:15], v223 offset:16768
	s_waitcnt lgkmcnt(8)
	v_add_f32_e32 v22, v0, v4
	v_sub_f32_e32 v24, v0, v4
	v_add_f32_e32 v26, v2, v6
	v_sub_f32_e32 v28, v2, v6
	v_add_f32_e32 v23, v1, v5
	v_sub_f32_e32 v25, v1, v5
	v_add_f32_e32 v27, v3, v7
	v_sub_f32_e32 v29, v3, v7
	v_add_f32_e32 v80, v22, v26
	v_add_f32_e32 v81, v23, v27
	ds_write_b64 v223, v[80:81] offset:0
	v_sub_f32_e32 v242, v22, v26
	v_sub_f32_e32 v243, v23, v27
	v_add_f32_e32 v244, v24, v29
	v_sub_f32_e32 v245, v25, v28
	v_sub_f32_e32 v246, v24, v29
	v_add_f32_e32 v247, v25, v28
	v_mul_f32_e32 v227, v245, v17
	v_fma_f32 v82, v244, v16, -v227
	v_mul_f32_e32 v227, v245, v16
	v_fma_f32 v83, v244, v17, v227
	ds_write_b64 v223, v[82:83] offset:128
	v_mul_f32_e32 v227, v243, v19
	v_fma_f32 v84, v242, v18, -v227
	v_mul_f32_e32 v227, v243, v18
	v_fma_f32 v85, v242, v19, v227
	ds_write_b64 v223, v[84:85] offset:256
	v_mul_f32_e32 v227, v247, v21
	v_fma_f32 v236, v246, v20, -v227
	v_mul_f32_e32 v227, v247, v20
	v_fma_f32 v237, v246, v21, v227
	ds_write_b64 v223, v[236:237] offset:384
	ds_read_b64 v[0:1], v223 offset:32768
	ds_read_b64 v[2:3], v223 offset:32896
	ds_read_b64 v[4:5], v223 offset:33024
	ds_read_b64 v[6:7], v223 offset:33152
	s_waitcnt lgkmcnt(8)
; HD float2 cmul(float2 a, float2 b){ return make_float2(a.x*b.x - a.y*b.y, a.x*b.y + a.y*b.x); }
; HD float2 cmulc(float2 a, float2 b){ return make_float2(a.x*b.x + a.y*b.y, a.y*b.x - a.x*b.y); }
; template<bool INV, bool NOTW>
; HD void bf4c(float2* Z, int i0, int i1, int i2, int i3, float2 w1, float2 w2, float2 w3){
;   float2 a0=Z[i0], a1=Z[i1], a2=Z[i2], a3=Z[i3];
;   if (INV && !NOTW){ a1=cmulc(a1,w1); a2=cmulc(a2,w2); a3=cmulc(a3,w3); }
;   float2 s02=make_float2(a0.x+a2.x,a0.y+a2.y), d02=make_float2(a0.x-a2.x,a0.y-a2.y);
;   float2 s13=make_float2(a1.x+a3.x,a1.y+a3.y), d13=make_float2(a1.x-a3.x,a1.y-a3.y);
;   float2 y0=make_float2(s02.x+s13.x,s02.y+s13.y), y2=make_float2(s02.x-s13.x,s02.y-s13.y);
;   float2 ym=make_float2(d02.x+d13.y,d02.y-d13.x);
;   float2 yp=make_float2(d02.x-d13.y,d02.y+d13.x);
;   float2 y1, y3;
;   if (INV){ y1=yp; y3=ym; } else if (NOTW){ y1=ym; y3=yp; } else { y1=cmul(ym,w1); y2=cmul(y2,w2); y3=cmul(yp,w3); }
;   Z[i0]=y0; Z[i1]=y1; Z[i2]=y2; Z[i3]=y3;
; }
; template<bool INV, int LQ, bool BARRIER=true>
; HD void fft_pass(float2* Z, const float2* twA, const float2* twB, int tid){
;     ...
;   } else {
;     int j=tid&(q-1); int base0=((tid>>LQ)<<(LQ+2))+j;
;     float2 w1=make_float2(1.f,0.f), w2=w1, w3=w1;
;     if (LQ>0){ int k=j*tws; w1=cmul(twA[k>>6],twB[k&63]); w2=cmul(w1,w1); w3=cmul(w2,w1); }
;     _Pragma("unroll") for (int i=0;i<8;++i){ int base=base0+i*2048; bf4c<INV,(LQ==0)>(Z,base,base+q,base+2*q,base+3*q,w1,w2,w3); }
;   }
;   if (BARRIER) __syncthreads(); else asm volatile("s_waitcnt lgkmcnt(0)" ::: "memory");
	v_add_f32_e32 v22, v8, v12
	v_sub_f32_e32 v24, v8, v12
	v_add_f32_e32 v26, v10, v14
	v_sub_f32_e32 v28, v10, v14
	v_add_f32_e32 v23, v9, v13
	v_sub_f32_e32 v25, v9, v13
	v_add_f32_e32 v27, v11, v15
	v_sub_f32_e32 v29, v11, v15
	v_add_f32_e32 v80, v22, v26
	v_add_f32_e32 v81, v23, v27
	ds_write_b64 v223, v[80:81] offset:16384
	v_sub_f32_e32 v242, v22, v26
	v_sub_f32_e32 v243, v23, v27
	v_add_f32_e32 v244, v24, v29
	v_sub_f32_e32 v245, v25, v28
	v_sub_f32_e32 v246, v24, v29
	v_add_f32_e32 v247, v25, v28
	v_mul_f32_e32 v227, v245, v17
	v_fma_f32 v82, v244, v16, -v227
	v_mul_f32_e32 v227, v245, v16
	v_fma_f32 v83, v244, v17, v227
	ds_write_b64 v223, v[82:83] offset:16512
	v_mul_f32_e32 v227, v243, v19
	v_fma_f32 v84, v242, v18, -v227
	v_mul_f32_e32 v227, v243, v18
	v_fma_f32 v85, v242, v19, v227
	ds_write_b64 v223, v[84:85] offset:16640
	v_mul_f32_e32 v227, v247, v21
	v_fma_f32 v236, v246, v20, -v227
	v_mul_f32_e32 v227, v247, v20
	v_fma_f32 v237, v246, v21, v227
	ds_write_b64 v223, v[236:237] offset:16768
	ds_read_b64 v[8:9], v223 offset:49152
	ds_read_b64 v[10:11], v223 offset:49280
	ds_read_b64 v[12:13], v223 offset:49408
	ds_read_b64 v[14:15], v223 offset:49536
	s_waitcnt lgkmcnt(8)
	v_add_f32_e32 v22, v0, v4
	v_sub_f32_e32 v24, v0, v4
	v_add_f32_e32 v26, v2, v6
	v_sub_f32_e32 v28, v2, v6
	v_add_f32_e32 v23, v1, v5
	v_sub_f32_e32 v25, v1, v5
	v_add_f32_e32 v27, v3, v7
	v_sub_f32_e32 v29, v3, v7
	v_add_f32_e32 v80, v22, v26
	v_add_f32_e32 v81, v23, v27
	ds_write_b64 v223, v[80:81] offset:32768
	v_sub_f32_e32 v242, v22, v26
	v_sub_f32_e32 v243, v23, v27
	v_add_f32_e32 v244, v24, v29
	v_sub_f32_e32 v245, v25, v28
	v_sub_f32_e32 v246, v24, v29
	v_add_f32_e32 v247, v25, v28
	v_mul_f32_e32 v227, v245, v17
	v_fma_f32 v82, v244, v16, -v227
	v_mul_f32_e32 v227, v245, v16
	v_fma_f32 v83, v244, v17, v227
	ds_write_b64 v223, v[82:83] offset:32896
	v_mul_f32_e32 v227, v243, v19
	v_fma_f32 v84, v242, v18, -v227
	v_mul_f32_e32 v227, v243, v18
	v_fma_f32 v85, v242, v19, v227
	ds_write_b64 v223, v[84:85] offset:33024
	v_mul_f32_e32 v227, v247, v21
	v_fma_f32 v236, v246, v20, -v227
	v_mul_f32_e32 v227, v247, v20
	v_fma_f32 v237, v246, v21, v227
	ds_write_b64 v223, v[236:237] offset:33152
	s_waitcnt lgkmcnt(4)
	v_add_f32_e32 v22, v8, v12
	v_sub_f32_e32 v24, v8, v12
	v_add_f32_e32 v26, v10, v14
	v_sub_f32_e32 v28, v10, v14
	v_add_f32_e32 v23, v9, v13
	v_sub_f32_e32 v25, v9, v13
	v_add_f32_e32 v27, v11, v15
	v_sub_f32_e32 v29, v11, v15
	v_add_f32_e32 v80, v22, v26
	v_add_f32_e32 v81, v23, v27
	ds_write_b64 v223, v[80:81] offset:49152
	v_sub_f32_e32 v242, v22, v26
	v_sub_f32_e32 v243, v23, v27
	v_add_f32_e32 v244, v24, v29
	v_sub_f32_e32 v245, v25, v28
	v_sub_f32_e32 v246, v24, v29
	v_add_f32_e32 v247, v25, v28
	v_mul_f32_e32 v227, v245, v17
	v_fma_f32 v82, v244, v16, -v227
	v_mul_f32_e32 v227, v245, v16
	v_fma_f32 v83, v244, v17, v227
	ds_write_b64 v223, v[82:83] offset:49280
	v_mul_f32_e32 v227, v243, v19
	v_fma_f32 v84, v242, v18, -v227
	v_mul_f32_e32 v227, v243, v18
	v_fma_f32 v85, v242, v19, v227
	ds_write_b64 v223, v[84:85] offset:49408
	v_mul_f32_e32 v227, v247, v21
	v_fma_f32 v236, v246, v20, -v227
	v_mul_f32_e32 v227, v247, v20
	v_fma_f32 v237, v246, v21, v227
	ds_write_b64 v223, v[236:237] offset:49536
	s_waitcnt lgkmcnt(0)
	v_and_b32_e32 v226, 3, v154
	v_lshlrev_b32_e32 v224, 7, v226
	v_add_u32_e32 v224, 0x20800, v224
	v_mov_b32_e32 v225, 0x20a00
	ds_read_b64 v[238:239], v224
	ds_read_b64 v[240:241], v225
	s_waitcnt lgkmcnt(0)
	v_mul_f32_e32 v227, v239, v241
	v_fma_f32 v16, v238, v240, -v227
	v_mul_f32_e32 v227, v239, v240
	v_fma_f32 v17, v238, v241, v227
	v_mul_f32_e32 v227, v17, v17
	v_fma_f32 v18, v16, v16, -v227
	v_mul_f32_e32 v227, v17, v16
	v_fma_f32 v19, v16, v17, v227
	v_mul_f32_e32 v227, v19, v17
	v_fma_f32 v20, v18, v16, -v227
	v_mul_f32_e32 v227, v19, v16
	v_fma_f32 v21, v18, v17, v227
	v_lshrrev_b32_e32 v222, 2, v154
	v_lshlrev_b32_e32 v222, 4, v222
	v_add_u32_e32 v222, v222, v226
	v_lshlrev_b32_e32 v222, 3, v222
	v_add_u32_e32 v223, 0x10000, v222
	ds_read_b64 v[0:1], v222 offset:0
	ds_read_b64 v[2:3], v222 offset:32
	ds_read_b64 v[4:5], v222 offset:64
	ds_read_b64 v[6:7], v222 offset:96
	ds_read_b64 v[8:9], v222 offset:16384
	ds_read_b64 v[10:11], v222 offset:16416
	ds_read_b64 v[12:13], v222 offset:16448
	ds_read_b64 v[14:15], v222 offset:16480
	s_waitcnt lgkmcnt(4)
	v_add_f32_e32 v22, v0, v4
	v_sub_f32_e32 v24, v0, v4
	v_add_f32_e32 v26, v2, v6
	v_sub_f32_e32 v28, v2, v6
	v_add_f32_e32 v23, v1, v5
	v_sub_f32_e32 v25, v1, v5
	v_add_f32_e32 v27, v3, v7
	v_sub_f32_e32 v29, v3, v7
	v_add_f32_e32 v80, v22, v26
	v_add_f32_e32 v81, v23, v27
	ds_write_b64 v222, v[80:81] offset:0
	v_sub_f32_e32 v242, v22, v26
	v_sub_f32_e32 v243, v23, v27
	v_add_f32_e32 v244, v24, v29
	v_sub_f32_e32 v245, v25, v28
	v_sub_f32_e32 v246, v24, v29
	v_add_f32_e32 v247, v25, v28
	v_mul_f32_e32 v227, v245, v17
	v_fma_f32 v82, v244, v16, -v227
	v_mul_f32_e32 v227, v245, v16
	v_fma_f32 v83, v244, v17, v227
	ds_write_b64 v222, v[82:83] offset:32
	v_mul_f32_e32 v227, v243, v19
	v_fma_f32 v84, v242, v18, -v227
	v_mul_f32_e32 v227, v243, v18
	v_fma_f32 v85, v242, v19, v227
	ds_write_b64 v222, v[84:85] offset:64
	v_mul_f32_e32 v227, v247, v21
	v_fma_f32 v236, v246, v20, -v227
	v_mul_f32_e32 v227, v247, v20
	v_fma_f32 v237, v246, v21, v227
	ds_write_b64 v222, v[236:237] offset:96
	ds_read_b64 v[0:1], v222 offset:32768
	ds_read_b64 v[2:3], v222 offset:32800
	ds_read_b64 v[4:5], v222 offset:32832
	ds_read_b64 v[6:7], v222 offset:32864
	s_waitcnt lgkmcnt(8)
; HD float2 cmul(float2 a, float2 b){ return make_float2(a.x*b.x - a.y*b.y, a.x*b.y + a.y*b.x); }
; HD float2 cmulc(float2 a, float2 b){ return make_float2(a.x*b.x + a.y*b.y, a.y*b.x - a.x*b.y); }
; template<bool INV, bool NOTW>
; HD void bf4c(float2* Z, int i0, int i1, int i2, int i3, float2 w1, float2 w2, float2 w3){
;   float2 a0=Z[i0], a1=Z[i1], a2=Z[i2], a3=Z[i3];
;   if (INV && !NOTW){ a1=cmulc(a1,w1); a2=cmulc(a2,w2); a3=cmulc(a3,w3); }
;   float2 s02=make_float2(a0.x+a2.x,a0.y+a2.y), d02=make_float2(a0.x-a2.x,a0.y-a2.y);
;   float2 s13=make_float2(a1.x+a3.x,a1.y+a3.y), d13=make_float2(a1.x-a3.x,a1.y-a3.y);
;   float2 y0=make_float2(s02.x+s13.x,s02.y+s13.y), y2=make_float2(s02.x-s13.x,s02.y-s13.y);
;   float2 ym=make_float2(d02.x+d13.y,d02.y-d13.x);
;   float2 yp=make_float2(d02.x-d13.y,d02.y+d13.x);
;   float2 y1, y3;
;   if (INV){ y1=yp; y3=ym; } else if (NOTW){ y1=ym; y3=yp; } else { y1=cmul(ym,w1); y2=cmul(y2,w2); y3=cmul(yp,w3); }
;   Z[i0]=y0; Z[i1]=y1; Z[i2]=y2; Z[i3]=y3;
; }
; template<bool INV, int LQ, bool BARRIER=true>
; HD void fft_pass(float2* Z, const float2* twA, const float2* twB, int tid){
;     ...
;   } else {
;     int j=tid&(q-1); int base0=((tid>>LQ)<<(LQ+2))+j;
;     float2 w1=make_float2(1.f,0.f), w2=w1, w3=w1;
;     if (LQ>0){ int k=j*tws; w1=cmul(twA[k>>6],twB[k&63]); w2=cmul(w1,w1); w3=cmul(w2,w1); }
;     _Pragma("unroll") for (int i=0;i<8;++i){ int base=base0+i*2048; bf4c<INV,(LQ==0)>(Z,base,base+q,base+2*q,base+3*q,w1,w2,w3); }
;   }
;   if (BARRIER) __syncthreads(); else asm volatile("s_waitcnt lgkmcnt(0)" ::: "memory");
	v_add_f32_e32 v22, v8, v12
	v_sub_f32_e32 v24, v8, v12
	v_add_f32_e32 v26, v10, v14
	v_sub_f32_e32 v28, v10, v14
	v_add_f32_e32 v23, v9, v13
	v_sub_f32_e32 v25, v9, v13
	v_add_f32_e32 v27, v11, v15
	v_sub_f32_e32 v29, v11, v15
	v_add_f32_e32 v80, v22, v26
	v_add_f32_e32 v81, v23, v27
	ds_write_b64 v222, v[80:81] offset:16384
	v_sub_f32_e32 v242, v22, v26
	v_sub_f32_e32 v243, v23, v27
	v_add_f32_e32 v244, v24, v29
	v_sub_f32_e32 v245, v25, v28
	v_sub_f32_e32 v246, v24, v29
	v_add_f32_e32 v247, v25, v28
	v_mul_f32_e32 v227, v245, v17
	v_fma_f32 v82, v244, v16, -v227
	v_mul_f32_e32 v227, v245, v16
	v_fma_f32 v83, v244, v17, v227
	ds_write_b64 v222, v[82:83] offset:16416
	v_mul_f32_e32 v227, v243, v19
	v_fma_f32 v84, v242, v18, -v227
	v_mul_f32_e32 v227, v243, v18
	v_fma_f32 v85, v242, v19, v227
	ds_write_b64 v222, v[84:85] offset:16448
	v_mul_f32_e32 v227, v247, v21
	v_fma_f32 v236, v246, v20, -v227
	v_mul_f32_e32 v227, v247, v20
	v_fma_f32 v237, v246, v21, v227
	ds_write_b64 v222, v[236:237] offset:16480
	ds_read_b64 v[8:9], v222 offset:49152
	ds_read_b64 v[10:11], v222 offset:49184
	ds_read_b64 v[12:13], v222 offset:49216
	ds_read_b64 v[14:15], v222 offset:49248
	s_waitcnt lgkmcnt(8)
	v_add_f32_e32 v22, v0, v4
	v_sub_f32_e32 v24, v0, v4
	v_add_f32_e32 v26, v2, v6
	v_sub_f32_e32 v28, v2, v6
	v_add_f32_e32 v23, v1, v5
	v_sub_f32_e32 v25, v1, v5
	v_add_f32_e32 v27, v3, v7
	v_sub_f32_e32 v29, v3, v7
	v_add_f32_e32 v80, v22, v26
	v_add_f32_e32 v81, v23, v27
	ds_write_b64 v222, v[80:81] offset:32768
	v_sub_f32_e32 v242, v22, v26
	v_sub_f32_e32 v243, v23, v27
	v_add_f32_e32 v244, v24, v29
	v_sub_f32_e32 v245, v25, v28
	v_sub_f32_e32 v246, v24, v29
	v_add_f32_e32 v247, v25, v28
	v_mul_f32_e32 v227, v245, v17
	v_fma_f32 v82, v244, v16, -v227
	v_mul_f32_e32 v227, v245, v16
	v_fma_f32 v83, v244, v17, v227
	ds_write_b64 v222, v[82:83] offset:32800
	v_mul_f32_e32 v227, v243, v19
	v_fma_f32 v84, v242, v18, -v227
	v_mul_f32_e32 v227, v243, v18
	v_fma_f32 v85, v242, v19, v227
	ds_write_b64 v222, v[84:85] offset:32832
	v_mul_f32_e32 v227, v247, v21
	v_fma_f32 v236, v246, v20, -v227
	v_mul_f32_e32 v227, v247, v20
	v_fma_f32 v237, v246, v21, v227
	ds_write_b64 v222, v[236:237] offset:32864
	ds_read_b64 v[0:1], v223 offset:0
	ds_read_b64 v[2:3], v223 offset:32
	ds_read_b64 v[4:5], v223 offset:64
	ds_read_b64 v[6:7], v223 offset:96
	s_waitcnt lgkmcnt(8)
	v_add_f32_e32 v22, v8, v12
	v_sub_f32_e32 v24, v8, v12
	v_add_f32_e32 v26, v10, v14
	v_sub_f32_e32 v28, v10, v14
	v_add_f32_e32 v23, v9, v13
	v_sub_f32_e32 v25, v9, v13
	v_add_f32_e32 v27, v11, v15
	v_sub_f32_e32 v29, v11, v15
	v_add_f32_e32 v80, v22, v26
	v_add_f32_e32 v81, v23, v27
	ds_write_b64 v222, v[80:81] offset:49152
	v_sub_f32_e32 v242, v22, v26
	v_sub_f32_e32 v243, v23, v27
	v_add_f32_e32 v244, v24, v29
	v_sub_f32_e32 v245, v25, v28
	v_sub_f32_e32 v246, v24, v29
	v_add_f32_e32 v247, v25, v28
	v_mul_f32_e32 v227, v245, v17
	v_fma_f32 v82, v244, v16, -v227
	v_mul_f32_e32 v227, v245, v16
	v_fma_f32 v83, v244, v17, v227
	ds_write_b64 v222, v[82:83] offset:49184
	v_mul_f32_e32 v227, v243, v19
	v_fma_f32 v84, v242, v18, -v227
	v_mul_f32_e32 v227, v243, v18
	v_fma_f32 v85, v242, v19, v227
	ds_write_b64 v222, v[84:85] offset:49216
	v_mul_f32_e32 v227, v247, v21
	v_fma_f32 v236, v246, v20, -v227
	v_mul_f32_e32 v227, v247, v20
	v_fma_f32 v237, v246, v21, v227
	ds_write_b64 v222, v[236:237] offset:49248
	ds_read_b64 v[8:9], v223 offset:16384
	ds_read_b64 v[10:11], v223 offset:16416
	ds_read_b64 v[12:13], v223 offset:16448
	ds_read_b64 v[14:15], v223 offset:16480
	s_waitcnt lgkmcnt(8)
	v_add_f32_e32 v22, v0, v4
	v_sub_f32_e32 v24, v0, v4
	v_add_f32_e32 v26, v2, v6
	v_sub_f32_e32 v28, v2, v6
	v_add_f32_e32 v23, v1, v5
	v_sub_f32_e32 v25, v1, v5
	v_add_f32_e32 v27, v3, v7
	v_sub_f32_e32 v29, v3, v7
	v_add_f32_e32 v80, v22, v26
	v_add_f32_e32 v81, v23, v27
	ds_write_b64 v223, v[80:81] offset:0
	v_sub_f32_e32 v242, v22, v26
	v_sub_f32_e32 v243, v23, v27
	v_add_f32_e32 v244, v24, v29
	v_sub_f32_e32 v245, v25, v28
	v_sub_f32_e32 v246, v24, v29
	v_add_f32_e32 v247, v25, v28
	v_mul_f32_e32 v227, v245, v17
	v_fma_f32 v82, v244, v16, -v227
	v_mul_f32_e32 v227, v245, v16
	v_fma_f32 v83, v244, v17, v227
	ds_write_b64 v223, v[82:83] offset:32
	v_mul_f32_e32 v227, v243, v19
	v_fma_f32 v84, v242, v18, -v227
	v_mul_f32_e32 v227, v243, v18
	v_fma_f32 v85, v242, v19, v227
	ds_write_b64 v223, v[84:85] offset:64
	v_mul_f32_e32 v227, v247, v21
	v_fma_f32 v236, v246, v20, -v227
	v_mul_f32_e32 v227, v247, v20
	v_fma_f32 v237, v246, v21, v227
	ds_write_b64 v223, v[236:237] offset:96
	ds_read_b64 v[0:1], v223 offset:32768
	ds_read_b64 v[2:3], v223 offset:32800
	ds_read_b64 v[4:5], v223 offset:32832
	ds_read_b64 v[6:7], v223 offset:32864
	s_waitcnt lgkmcnt(8)
; HD float2 cmul(float2 a, float2 b){ return make_float2(a.x*b.x - a.y*b.y, a.x*b.y + a.y*b.x); }
; HD float2 cmulc(float2 a, float2 b){ return make_float2(a.x*b.x + a.y*b.y, a.y*b.x - a.x*b.y); }
; template<bool INV, bool NOTW>
; HD void bf4c(float2* Z, int i0, int i1, int i2, int i3, float2 w1, float2 w2, float2 w3){
;   float2 a0=Z[i0], a1=Z[i1], a2=Z[i2], a3=Z[i3];
;   if (INV && !NOTW){ a1=cmulc(a1,w1); a2=cmulc(a2,w2); a3=cmulc(a3,w3); }
;   float2 s02=make_float2(a0.x+a2.x,a0.y+a2.y), d02=make_float2(a0.x-a2.x,a0.y-a2.y);
;   float2 s13=make_float2(a1.x+a3.x,a1.y+a3.y), d13=make_float2(a1.x-a3.x,a1.y-a3.y);
;   float2 y0=make_float2(s02.x+s13.x,s02.y+s13.y), y2=make_float2(s02.x-s13.x,s02.y-s13.y);
;   float2 ym=make_float2(d02.x+d13.y,d02.y-d13.x);
;   float2 yp=make_float2(d02.x-d13.y,d02.y+d13.x);
;   float2 y1, y3;
;   if (INV){ y1=yp; y3=ym; } else if (NOTW){ y1=ym; y3=yp; } else { y1=cmul(ym,w1); y2=cmul(y2,w2); y3=cmul(yp,w3); }
;   Z[i0]=y0; Z[i1]=y1; Z[i2]=y2; Z[i3]=y3;
; }
; template<bool INV, int LQ, bool BARRIER=true>
; HD void fft_pass(float2* Z, const float2* twA, const float2* twB, int tid){
;     ...
;   } else {
;     int j=tid&(q-1); int base0=((tid>>LQ)<<(LQ+2))+j;
;     float2 w1=make_float2(1.f,0.f), w2=w1, w3=w1;
;     if (LQ>0){ int k=j*tws; w1=cmul(twA[k>>6],twB[k&63]); w2=cmul(w1,w1); w3=cmul(w2,w1); }
;     _Pragma("unroll") for (int i=0;i<8;++i){ int base=base0+i*2048; bf4c<INV,(LQ==0)>(Z,base,base+q,base+2*q,base+3*q,w1,w2,w3); }
;   }
;   if (BARRIER) __syncthreads(); else asm volatile("s_waitcnt lgkmcnt(0)" ::: "memory");
	v_add_f32_e32 v22, v8, v12
	v_sub_f32_e32 v24, v8, v12
	v_add_f32_e32 v26, v10, v14
	v_sub_f32_e32 v28, v10, v14
	v_add_f32_e32 v23, v9, v13
	v_sub_f32_e32 v25, v9, v13
	v_add_f32_e32 v27, v11, v15
	v_sub_f32_e32 v29, v11, v15
	v_add_f32_e32 v80, v22, v26
	v_add_f32_e32 v81, v23, v27
	ds_write_b64 v223, v[80:81] offset:16384
	v_sub_f32_e32 v242, v22, v26
	v_sub_f32_e32 v243, v23, v27
	v_add_f32_e32 v244, v24, v29
	v_sub_f32_e32 v245, v25, v28
	v_sub_f32_e32 v246, v24, v29
	v_add_f32_e32 v247, v25, v28
	v_mul_f32_e32 v227, v245, v17
	v_fma_f32 v82, v244, v16, -v227
	v_mul_f32_e32 v227, v245, v16
	v_fma_f32 v83, v244, v17, v227
	ds_write_b64 v223, v[82:83] offset:16416
	v_mul_f32_e32 v227, v243, v19
	v_fma_f32 v84, v242, v18, -v227
	v_mul_f32_e32 v227, v243, v18
	v_fma_f32 v85, v242, v19, v227
	ds_write_b64 v223, v[84:85] offset:16448
	v_mul_f32_e32 v227, v247, v21
	v_fma_f32 v236, v246, v20, -v227
	v_mul_f32_e32 v227, v247, v20
	v_fma_f32 v237, v246, v21, v227
	ds_write_b64 v223, v[236:237] offset:16480
	ds_read_b64 v[8:9], v223 offset:49152
	ds_read_b64 v[10:11], v223 offset:49184
	ds_read_b64 v[12:13], v223 offset:49216
	ds_read_b64 v[14:15], v223 offset:49248
	s_waitcnt lgkmcnt(8)
	v_add_f32_e32 v22, v0, v4
	v_sub_f32_e32 v24, v0, v4
	v_add_f32_e32 v26, v2, v6
	v_sub_f32_e32 v28, v2, v6
	v_add_f32_e32 v23, v1, v5
	v_sub_f32_e32 v25, v1, v5
	v_add_f32_e32 v27, v3, v7
	v_sub_f32_e32 v29, v3, v7
	v_add_f32_e32 v80, v22, v26
	v_add_f32_e32 v81, v23, v27
	ds_write_b64 v223, v[80:81] offset:32768
	v_sub_f32_e32 v242, v22, v26
	v_sub_f32_e32 v243, v23, v27
	v_add_f32_e32 v244, v24, v29
	v_sub_f32_e32 v245, v25, v28
	v_sub_f32_e32 v246, v24, v29
	v_add_f32_e32 v247, v25, v28
	v_mul_f32_e32 v227, v245, v17
	v_fma_f32 v82, v244, v16, -v227
	v_mul_f32_e32 v227, v245, v16
	v_fma_f32 v83, v244, v17, v227
	ds_write_b64 v223, v[82:83] offset:32800
	v_mul_f32_e32 v227, v243, v19
	v_fma_f32 v84, v242, v18, -v227
	v_mul_f32_e32 v227, v243, v18
	v_fma_f32 v85, v242, v19, v227
	ds_write_b64 v223, v[84:85] offset:32832
	v_mul_f32_e32 v227, v247, v21
	v_fma_f32 v236, v246, v20, -v227
	v_mul_f32_e32 v227, v247, v20
	v_fma_f32 v237, v246, v21, v227
	ds_write_b64 v223, v[236:237] offset:32864
	s_waitcnt lgkmcnt(4)
	v_add_f32_e32 v22, v8, v12
	v_sub_f32_e32 v24, v8, v12
	v_add_f32_e32 v26, v10, v14
	v_sub_f32_e32 v28, v10, v14
	v_add_f32_e32 v23, v9, v13
	v_sub_f32_e32 v25, v9, v13
	v_add_f32_e32 v27, v11, v15
	v_sub_f32_e32 v29, v11, v15
	v_add_f32_e32 v80, v22, v26
	v_add_f32_e32 v81, v23, v27
	ds_write_b64 v223, v[80:81] offset:49152
	v_sub_f32_e32 v242, v22, v26
	v_sub_f32_e32 v243, v23, v27
	v_add_f32_e32 v244, v24, v29
	v_sub_f32_e32 v245, v25, v28
	v_sub_f32_e32 v246, v24, v29
	v_add_f32_e32 v247, v25, v28
	v_mul_f32_e32 v227, v245, v17
	v_fma_f32 v82, v244, v16, -v227
	v_mul_f32_e32 v227, v245, v16
	v_fma_f32 v83, v244, v17, v227
	ds_write_b64 v223, v[82:83] offset:49184
	v_mul_f32_e32 v227, v243, v19
	v_fma_f32 v84, v242, v18, -v227
	v_mul_f32_e32 v227, v243, v18
	v_fma_f32 v85, v242, v19, v227
	ds_write_b64 v223, v[84:85] offset:49216
	v_mul_f32_e32 v227, v247, v21
	v_fma_f32 v236, v246, v20, -v227
	v_mul_f32_e32 v227, v247, v20
	v_fma_f32 v237, v246, v21, v227
	ds_write_b64 v223, v[236:237] offset:49248
	s_waitcnt lgkmcnt(0)
	v_add_u32_e32 v14, 0x4000, v169
	v_add_u32_e32 v15, 0x8000, v169
	v_add_u32_e32 v16, 0xc000, v169
	v_add_u32_e32 v17, 0x4000, v186
	v_add_u32_e32 v18, 0x8000, v186
	v_add_u32_e32 v19, 0xc000, v186
	s_mov_b64 s[12:13], -1
	s_and_b64 vcc, exec, s[68:69]
	s_cbranch_vccz .LBB0_1344
	s_cmp_lg_u32 s89, 1
	s_cselect_b64 s[50:51], -1, 0
	s_cmp_eq_u32 s89, 1
	s_cselect_b32 s69, s77, s79
	s_cselect_b32 s68, s76, s78
	v_lshl_add_u64 v[0:1], s[68:69], 0, v[74:75]
	s_mov_b32 s12, 0
	v_mov_b32_e32 v2, v217
